# phase8 scanC: per-wave column-slice decomposition, state/gate/onorm prefetched after first barrier, batched epilogue
# speedup vs baseline: 1.7425x; 1.7425x over previous
.LBB0_1335:
	s_cmp_lt_i32 s94, 9
	s_cselect_b64 s[22:23], -1, 0
	s_and_b64 s[0:1], s[22:23], s[2:3]
	s_xor_b64 s[0:1], s[0:1], -1
	s_cmpk_gt_i32 s97, 0xbff
	s_cselect_b64 s[2:3], -1, 0
	s_or_b64 s[0:1], s[2:3], s[0:1]
	s_and_b64 vcc, exec, s[0:1]
	s_cbranch_vccnz .LBB0_1405
	v_and_b32_e32 v134, 0x7f, v0
	v_bfe_u32 v3, v0, 4, 2
	s_movk_i32 s0, 0x200
	s_waitcnt lgkmcnt(0)
	v_or_b32_e32 v5, 0x200, v0
	v_lshlrev_b32_e32 v8, 1, v134
	v_lshrrev_b32_e32 v1, 7, v0
	v_lshrrev_b32_e32 v5, 2, v5
	v_lshlrev_b32_e32 v138, 2, v3
	s_movk_i32 s1, 0x1100
	v_add_u32_e32 v178, 0, v8
	v_cmp_gt_u32_e64 s[8:9], s0, v0
	s_add_i32 s0, 0, 0x16000
	v_lshlrev_b32_e32 v140, 3, v3
	v_lshlrev_b32_e32 v183, 4, v3
	s_add_i32 s20, 0, 0x13c00
	v_cmp_eq_u32_e64 s[18:19], 0, v3
	v_lshrrev_b32_e32 v3, 3, v0
	v_and_b32_e32 v139, 15, v0
	v_and_b32_e32 v6, 0xf8, v5
	v_lshlrev_b32_e32 v5, 2, v0
	v_mad_u32_u24 v179, v1, s1, v178
	s_movk_i32 s1, 0x100
	s_movk_i32 s43, 0x110
	v_and_b32_e32 v188, 48, v3
	s_add_u32 s26, s92, 0xe400000
	v_lshlrev_b32_e32 v3, 4, v0
	v_mov_b32_e32 v137, 0
	v_add_u32_e32 v141, 0, v5
	v_cmp_gt_u32_e64 s[4:5], s1, v0
	s_movk_i32 s1, 0x180
	v_and_b32_e32 v181, 0x7c, v5
	v_mov_b32_e32 v5, s0
	v_mad_u32_u24 v185, v139, s43, 0
	v_add_u32_e32 v186, s0, v183
	s_movk_i32 s0, 0xfef4
	s_addc_u32 s27, s93, 0
	v_and_b32_e32 v136, 0x3f0, v3
	v_lshlrev_b32_e32 v2, 1, v0
	v_cmp_gt_u32_e64 s[6:7], s1, v0
	v_or_b32_e32 v9, 1, v138
	v_mad_i32_i24 v187, v139, s0, v185
	s_add_u32 s44, s90, 0x4000000
	v_lshl_add_u64 v[10:11], s[92:93], 0, v[136:137]
	s_mov_b64 s[0:1], 0x1cc90000
	v_and_b32_e32 v2, 62, v2
	v_lshrrev_b32_e32 v4, 2, v0
	v_cmp_gt_u32_e64 s[12:13], v139, v9
	v_or_b32_e32 v9, 2, v138
	s_addc_u32 s45, s91, 0
	v_lshl_add_u64 v[144:145], v[10:11], 0, s[0:1]
	s_lshl_b32 s0, s97, 7
	v_mul_u32_u24_e32 v2, 0x1d00, v2
	v_and_b32_e32 v4, 0x78, v4
	v_lshl_add_u32 v143, v134, 2, 0
	s_movk_i32 s42, 0x90
	v_cmp_gt_u32_e64 s[14:15], v139, v9
	v_or_b32_e32 v9, 3, v138
	s_add_i32 s46, s0, 0x1400
	s_lshl_b32 s0, s97, 8
	v_sub_u32_e32 v7, v143, v8
	v_mul_u32_u24_e32 v12, 0x1100, v1
	s_movk_i32 s2, 0x80
	v_add_u32_e32 v13, 0xf800, v178
	v_mad_u32_u24 v182, v4, s42, v5
	v_mad_u32_u24 v5, v6, s42, v5
	v_cmp_gt_u32_e64 s[16:17], v139, v9
	v_mov_b32_e32 v9, v137
	s_add_i32 s49, s0, 0x1000
	s_lshl_b32 s0, s97, 15
	v_lshlrev_b32_e32 v152, 1, v2
	v_mbcnt_lo_u32_b32 v2, -1, 0
	v_lshlrev_b32_e32 v135, 4, v1
	s_mov_b32 s25, 0
	v_cmp_gt_u32_e64 s[2:3], s2, v0
	v_add_u32_e32 v180, 0xf800, v179
	v_lshl_add_u32 v184, v139, 1, s20
	v_cmp_gt_u32_e64 s[10:11], v139, v138
	v_add_u32_e32 v142, 0, v183
	v_lshl_add_u64 v[146:147], s[26:27], 0, v[8:9]
	v_add_u32_e32 v189, s20, v183
	v_add_u32_e32 v190, 64, v186
	s_lshl_b32 s47, s96, 7
	s_movk_i32 s48, 0x1000
	s_lshl_b32 s50, s96, 8
	s_add_i32 s51, s0, 0xfffc0000
	s_lshl_b32 s52, s96, 15
	s_movk_i32 s53, 0x3a00
	v_lshlrev_b32_e32 v148, 1, v6
	s_movk_i32 s54, 0x2000
	s_movk_i32 s55, 0x3000
	s_movk_i32 s56, 0x4000
	s_movk_i32 s57, 0x5000
	s_movk_i32 s58, 0x6000
	s_movk_i32 s59, 0x7000
	s_mov_b64 s[28:29], 0xe401c00
	s_mov_b32 s60, 0xbfb8aa3b
	s_mov_b32 s61, 0x800000
	s_mov_b32 s62, 0x3f317217
	s_mov_b32 s63, 0x7f800000
	s_mov_b32 s64, 0x3d800000
	s_mov_b64 s[30:31], 0x2000
	s_mov_b32 s65, 0x3fb8aa3b
	v_add_u32_e32 v191, v7, v12
	s_mov_b32 s66, 0xffff0000
	v_add_u32_e32 v192, v5, v181
	v_mov_b32_e32 v193, 0x358637bd
	s_mov_b64 s[34:35], 0x1000
	v_add_u32_e32 v194, v13, v12
	v_lshlrev_b32_e32 v150, 1, v134
	v_lshlrev_b32_e32 v154, 1, v4
	v_mov_b32_e32 v195, 0x41b17218
	v_lshlrev_b32_e32 v156, 1, v138
	v_mbcnt_hi_u32_b32 v196, -1, v2
	s_mov_b32 s67, s97
	s_branch .LBB0_1339
.LBB0_1338:
	s_add_i32 s67, s67, s96
	s_add_i32 s46, s46, s47
	s_add_i32 s49, s49, s50
	s_add_i32 s51, s51, s52
	s_cmpk_lt_i32 s67, 0xc00
	s_waitcnt vmcnt(63) expcnt(7) lgkmcnt(15)
	s_cbranch_scc0 .LBB0_1404
.LBB0_1339:
	s_mul_hi_i32 s0, s67, 0x2aaaaaab
	s_lshr_b32 s1, s0, 31
	s_ashr_i32 s0, s0, 1
	s_add_i32 s20, s0, s1
	s_mul_i32 s0, s20, -12
	s_add_i32 s36, s67, s0
	s_mov_b64 s[0:1], -1
	s_cmp_gt_i32 s36, 7
	s_mul_i32 s37, s20, 0xfffffa00
	s_mul_i32 s68, s20, 0xe8000
	s_cbranch_scc0 .LBB0_1367
	s_add_i32 s0, s46, s37
	s_mul_i32 s1, s20, 0xfffff400
	s_addk_i32 s0, 0xe800
	s_add_i32 s38, s49, s1
	s_mov_b32 s1, s25
	s_add_i32 s24, s38, 0xffffe800
	s_lshl_b32 s21, s20, 6
	s_lshl_b64 s[40:41], s[0:1], 1
	s_add_u32 s40, s26, s40
	s_addc_u32 s41, s27, s41
	v_or_b32_e32 v20, s21, v135
	v_mov_b64_e32 v[2:3], s[40:41]
	v_mad_i64_i32 v[4:5], s[40:41], v20, s53, v[2:3]
	v_mov_b32_e32 v151, v137
	v_lshl_add_u64 v[4:5], v[4:5], 0, v[150:151]
	v_or_b32_e32 v21, 1, v20
	v_add_co_u32_e32 v4, vcc, s48, v4
	v_mad_i64_i32 v[6:7], s[40:41], v21, s53, v[2:3]
	s_nop 0
	v_addc_co_u32_e32 v5, vcc, 0, v5, vcc
	v_lshl_add_u64 v[6:7], v[6:7], 0, v[150:151]
	v_or_b32_e32 v31, 2, v20
	v_add_co_u32_e32 v6, vcc, s48, v6
	v_mad_i64_i32 v[8:9], s[40:41], v31, s53, v[2:3]
	s_nop 0
	v_addc_co_u32_e32 v7, vcc, 0, v7, vcc
	v_lshl_add_u64 v[8:9], v[8:9], 0, v[150:151]
	v_or_b32_e32 v32, 3, v20
	v_add_co_u32_e32 v8, vcc, s48, v8
	v_mad_i64_i32 v[10:11], s[40:41], v32, s53, v[2:3]
	s_nop 0
	v_addc_co_u32_e32 v9, vcc, 0, v9, vcc
	v_lshl_add_u64 v[10:11], v[10:11], 0, v[150:151]
	v_or_b32_e32 v33, 4, v20
	v_add_co_u32_e32 v10, vcc, s48, v10
	v_mad_i64_i32 v[12:13], s[40:41], v33, s53, v[2:3]
	s_nop 0
	v_addc_co_u32_e32 v11, vcc, 0, v11, vcc
	v_lshl_add_u64 v[12:13], v[12:13], 0, v[150:151]
	v_or_b32_e32 v34, 5, v20
	v_add_co_u32_e32 v12, vcc, s48, v12
	v_mad_i64_i32 v[14:15], s[40:41], v34, s53, v[2:3]
	s_nop 0
	v_addc_co_u32_e32 v13, vcc, 0, v13, vcc
	v_lshl_add_u64 v[14:15], v[14:15], 0, v[150:151]
	v_or_b32_e32 v35, 6, v20
	v_add_co_u32_e32 v14, vcc, s48, v14
	v_mad_i64_i32 v[16:17], s[40:41], v35, s53, v[2:3]
	s_nop 0
	v_addc_co_u32_e32 v15, vcc, 0, v15, vcc
	v_lshl_add_u64 v[16:17], v[16:17], 0, v[150:151]
	v_or_b32_e32 v36, 7, v20
	v_add_co_u32_e32 v16, vcc, s48, v16
	v_mad_i64_i32 v[18:19], s[40:41], v36, s53, v[2:3]
	s_nop 0
	v_addc_co_u32_e32 v17, vcc, 0, v17, vcc
	v_lshl_add_u64 v[18:19], v[18:19], 0, v[150:151]
	v_add_co_u32_e32 v18, vcc, s48, v18
	v_or_b32_e32 v37, 8, v20
	s_nop 0
	v_addc_co_u32_e32 v19, vcc, 0, v19, vcc
	global_load_ushort v22, v[4:5], off offset:2048
	s_nop 0
	global_load_ushort v6, v[6:7], off offset:2048
	s_nop 0
	global_load_ushort v7, v[8:9], off offset:2048
	s_nop 0
	global_load_ushort v8, v[10:11], off offset:2048
	global_load_ushort v9, v[12:13], off offset:2048
	s_nop 0
	global_load_ushort v10, v[14:15], off offset:2048
	global_load_ushort v11, v[16:17], off offset:2048
	global_load_ushort v12, v[18:19], off offset:2048
	v_mad_i64_i32 v[4:5], s[40:41], v37, s53, v[2:3]
	v_lshl_add_u64 v[4:5], v[4:5], 0, v[150:151]
	v_add_co_u32_e32 v4, vcc, s48, v4
	v_or_b32_e32 v38, 9, v20
	s_nop 0
	v_addc_co_u32_e32 v5, vcc, 0, v5, vcc
	global_load_ushort v16, v[4:5], off offset:2048
	v_mad_i64_i32 v[4:5], s[40:41], v38, s53, v[2:3]
	v_lshl_add_u64 v[4:5], v[4:5], 0, v[150:151]
	v_or_b32_e32 v39, 10, v20
	v_add_co_u32_e32 v4, vcc, s48, v4
	v_or_b32_e32 v40, 11, v20
	s_nop 0
	v_addc_co_u32_e32 v5, vcc, 0, v5, vcc
	v_or_b32_e32 v41, 12, v20
	v_or_b32_e32 v42, 13, v20
	v_or_b32_e32 v44, 14, v20
	v_mad_i64_i32 v[14:15], s[40:41], v44, s53, v[2:3]
	v_lshl_add_u64 v[14:15], v[14:15], 0, v[150:151]
	v_or_b32_e32 v46, 15, v20
	s_mul_hi_i32 s1, s21, 0x3a00
	s_add_u32 s33, s26, s68
	s_mov_b32 s39, s25
	v_add_u32_e32 v136, s0, v134
	s_addc_u32 s1, s27, s1
	v_readlane_b32 s72, v255, 13
	v_readlane_b32 s73, v255, 14
	v_readlane_b32 s74, v255, 15
	v_readlane_b32 s75, v255, 16
	v_readlane_b32 s76, v255, 17
	v_readlane_b32 s77, v255, 18
	v_readlane_b32 s78, v255, 19
	v_readlane_b32 s79, v255, 20
	v_readlane_b32 s80, v255, 21
	v_readlane_b32 s81, v255, 22
	v_readlane_b32 s82, v255, 23
	v_readlane_b32 s83, v255, 24
	v_readlane_b32 s84, v255, 25
	v_readlane_b32 s85, v255, 26
	s_mov_b64 s[72:73], s[76:77]
	s_mov_b64 s[74:75], s[78:79]
	s_mov_b64 s[76:77], s[80:81]
	s_mov_b64 s[78:79], s[82:83]
	v_mov_b32_e32 v153, v137
	v_mov_b32_e32 v155, v137
	v_mov_b32_e32 v149, v137
	v_readfirstlane_b32 s69, v0
	v_mov_b32_e32 v157, v137
	v_readlane_b32 s86, v255, 27
	v_readlane_b32 s87, v255, 28
	s_mov_b64 s[80:81], s[84:85]
	s_waitcnt vmcnt(0)
	v_lshlrev_b32_e32 v30, 16, v22
	v_lshlrev_b32_e32 v29, 16, v6
	v_lshlrev_b32_e32 v28, 16, v7
	v_mad_i64_i32 v[6:7], s[40:41], v39, s53, v[2:3]
	v_lshl_add_u64 v[6:7], v[6:7], 0, v[150:151]
	v_lshlrev_b32_e32 v27, 16, v8
	v_lshlrev_b32_e32 v25, 16, v9
	v_add_co_u32_e32 v6, vcc, s48, v6
	v_mad_i64_i32 v[8:9], s[40:41], v40, s53, v[2:3]
	s_nop 0
	v_addc_co_u32_e32 v7, vcc, 0, v7, vcc
	v_lshl_add_u64 v[8:9], v[8:9], 0, v[150:151]
	v_lshlrev_b32_e32 v24, 16, v10
	v_lshlrev_b32_e32 v23, 16, v11
	v_add_co_u32_e32 v8, vcc, s48, v8
	v_mad_i64_i32 v[10:11], s[40:41], v41, s53, v[2:3]
	s_nop 0
	v_addc_co_u32_e32 v9, vcc, 0, v9, vcc
	v_lshl_add_u64 v[10:11], v[10:11], 0, v[150:151]
	v_lshlrev_b32_e32 v22, 16, v12
	v_add_co_u32_e32 v10, vcc, s48, v10
	v_mad_i64_i32 v[12:13], s[40:41], v42, s53, v[2:3]
	s_nop 0
	v_addc_co_u32_e32 v11, vcc, 0, v11, vcc
	v_lshl_add_u64 v[12:13], v[12:13], 0, v[150:151]
	v_add_co_u32_e32 v12, vcc, s48, v12
	v_mad_i64_i32 v[2:3], s[40:41], v46, s53, v[2:3]
	s_nop 0
	v_addc_co_u32_e32 v13, vcc, 0, v13, vcc
	v_add_co_u32_e32 v14, vcc, s48, v14
	v_lshl_add_u64 v[2:3], v[2:3], 0, v[150:151]
	s_nop 0
	v_addc_co_u32_e32 v15, vcc, 0, v15, vcc
	v_add_co_u32_e32 v2, vcc, s48, v2
	s_lshl_b64 s[40:41], s[38:39], 1
	s_nop 0
	v_addc_co_u32_e32 v3, vcc, 0, v3, vcc
	global_load_ushort v43, v[4:5], off offset:2048
	global_load_ushort v45, v[6:7], off offset:2048
	global_load_ushort v47, v[8:9], off offset:2048
	global_load_ushort v48, v[10:11], off offset:2048
	global_load_ushort v52, v[12:13], off offset:2048
	global_load_ushort v54, v[14:15], off offset:2048
	global_load_ushort v59, v[2:3], off offset:2048
	v_lshl_add_u64 v[10:11], v[136:137], 1, s[92:93]
	s_add_u32 s40, s33, s40
	v_lshl_add_u64 v[72:73], v[10:11], 0, s[28:29]
	v_lshlrev_b32_e32 v26, 16, v16
	s_addc_u32 s41, s1, s41
	v_mad_i64_i32 v[10:11], s[0:1], v20, s53, v[72:73]
	v_mad_i64_i32 v[12:13], s[0:1], v21, s53, v[72:73]
	v_mad_i64_i32 v[14:15], s[0:1], v31, s53, v[72:73]
	v_mad_i64_i32 v[16:17], s[0:1], v32, s53, v[72:73]
	v_mad_i64_i32 v[18:19], s[0:1], v33, s53, v[72:73]
	v_mad_i64_i32 v[20:21], s[0:1], v34, s53, v[72:73]
	v_mad_i64_i32 v[32:33], s[0:1], v35, s53, v[72:73]
	v_mad_i64_i32 v[34:35], s[0:1], v36, s53, v[72:73]
	v_readfirstlane_b32 s0, v1
	s_lshl_b32 s0, s0, 4
	v_lshlrev_b64 v[2:3], 2, v[136:137]
	s_add_i32 s0, s0, s21
	v_lshl_add_u64 v[4:5], s[76:77], 0, v[2:3]
	s_ashr_i32 s1, s0, 31
	v_add_co_u32_e32 v6, vcc, s48, v4
	v_lshl_add_u64 v[2:3], s[78:79], 0, v[2:3]
	s_lshl_b64 s[0:1], s[0:1], 6
	v_addc_co_u32_e32 v7, vcc, 0, v5, vcc
	global_load_dword v51, v[4:5], off
	global_load_dword v50, v[4:5], off offset:2048
	global_load_dword v49, v[6:7], off offset:2048
	global_load_ushort v60, v[10:11], off
	global_load_ushort v64, v[12:13], off
	global_load_ushort v71, v[14:15], off
	global_load_ushort v74, v[16:17], off
	global_load_ushort v75, v[18:19], off
	global_load_ushort v76, v[20:21], off
	global_load_ushort v77, v[32:33], off
	global_load_ushort v78, v[34:35], off
	global_load_dword v53, v[2:3], off
	v_lshl_add_u64 v[2:3], v[144:145], 0, s[0:1]
	global_load_dwordx4 v[18:21], v[2:3], off
	v_add_co_u32_e32 v8, vcc, s54, v4
	s_bfe_u32 s71, s69, 0x20006
	s_nop 0
	v_addc_co_u32_e32 v9, vcc, 0, v5, vcc
	v_add_co_u32_e32 v6, vcc, s55, v4
	global_load_dword v70, v[8:9], off offset:-4096
	global_load_dword v68, v[8:9], off
	global_load_dword v65, v[8:9], off offset:2048
	v_addc_co_u32_e32 v7, vcc, 0, v5, vcc
	v_add_co_u32_e32 v2, vcc, s56, v4
	s_lshl_b32 s33, s71, 4
	s_nop 0
	v_addc_co_u32_e32 v3, vcc, 0, v5, vcc
	v_add_co_u32_e32 v8, vcc, s57, v4
	v_mul_f32_e32 v30, 0x3db504f3, v30
	s_nop 0
	v_addc_co_u32_e32 v9, vcc, 0, v5, vcc
	v_add_co_u32_e32 v10, vcc, s58, v4
	v_mul_f32_e32 v29, 0x3db504f3, v29
	s_nop 0
	v_addc_co_u32_e32 v11, vcc, 0, v5, vcc
	global_load_dword v66, v[6:7], off offset:2048
	global_load_dword v69, v[2:3], off offset:-4096
	global_load_dword v67, v[2:3], off
	global_load_dword v62, v[2:3], off offset:2048
	global_load_dword v61, v[10:11], off offset:-4096
	global_load_dword v58, v[10:11], off
	global_load_dword v56, v[10:11], off offset:2048
	v_add_co_u32_e32 v2, vcc, s59, v4
	v_mad_i64_i32 v[6:7], s[0:1], v39, s53, v[72:73]
	s_nop 0
	v_addc_co_u32_e32 v3, vcc, 0, v5, vcc
	global_load_dword v63, v[8:9], off offset:2048
	global_load_dword v57, v[2:3], off
	global_load_dword v55, v[2:3], off offset:2048
	v_mad_i64_i32 v[2:3], s[0:1], v37, s53, v[72:73]
	v_mad_i64_i32 v[4:5], s[0:1], v38, s53, v[72:73]
	global_load_ushort v38, v[2:3], off
	global_load_ushort v79, v[4:5], off
	global_load_ushort v80, v[6:7], off
	v_mad_i64_i32 v[2:3], s[0:1], v40, s53, v[72:73]
	v_mad_i64_i32 v[4:5], s[0:1], v41, s53, v[72:73]
	global_load_ushort v40, v[2:3], off
	global_load_ushort v81, v[4:5], off
	v_lshl_add_u64 v[2:3], s[40:41], 0, v[152:153]
	s_mov_b64 s[0:1], 0x3a00
	s_waitcnt vmcnt(37)
	v_lshlrev_b32_e32 v37, 16, v43
	s_waitcnt vmcnt(36)
	v_lshlrev_b32_e32 v36, 16, v45
	s_waitcnt vmcnt(35)
	v_lshlrev_b32_e32 v35, 16, v47
	v_lshl_add_u64 v[4:5], v[2:3], 0, s[0:1]
	s_waitcnt vmcnt(34)
	v_lshlrev_b32_e32 v34, 16, v48
	v_lshl_add_u64 v[6:7], v[2:3], 0, v[154:155]
	v_lshl_add_u64 v[8:9], v[4:5], 0, v[154:155]
	global_load_dwordx4 v[10:13], v[6:7], off
	global_load_dwordx4 v[14:17], v[8:9], off
	v_lshl_add_u64 v[2:3], v[2:3], 0, v[148:149]
	v_lshl_add_u64 v[6:7], v[4:5], 0, v[148:149]
	s_waitcnt vmcnt(35)
	v_lshlrev_b32_e32 v33, 16, v52
	s_waitcnt vmcnt(34)
	v_lshlrev_b32_e32 v32, 16, v54
	s_waitcnt vmcnt(33)
	v_lshlrev_b32_e32 v31, 16, v59
	global_load_dwordx4 v[2:5], v[2:3], off
	s_nop 0
	global_load_dwordx4 v[6:9], v[6:7], off
	v_or_b32_e32 v149, s33, v139
	v_mul_f32_e32 v28, 0x3db504f3, v28
	v_mul_f32_e32 v27, 0x3db504f3, v27
	v_mul_f32_e32 v25, 0x3db504f3, v25
	v_mul_f32_e32 v24, 0x3db504f3, v24
	v_mul_f32_e32 v23, 0x3db504f3, v23
	v_mul_f32_e32 v22, 0x3db504f3, v22
	v_mul_f32_e32 v26, 0x3db504f3, v26
	v_mul_f32_e32 v36, 0x3db504f3, v36
	v_mul_f32_e32 v35, 0x3db504f3, v35
	s_waitcnt vmcnt(31)
	v_lshlrev_b32_e32 v54, 16, v60
	s_waitcnt vmcnt(30)
	v_lshlrev_b32_e32 v52, 16, v64
	s_waitcnt vmcnt(29)
	v_lshlrev_b32_e32 v48, 16, v71
	s_waitcnt vmcnt(28)
	v_lshlrev_b32_e32 v47, 16, v74
	s_waitcnt vmcnt(27)
	v_lshlrev_b32_e32 v45, 16, v75
	s_waitcnt vmcnt(26)
	v_lshlrev_b32_e32 v43, 16, v76
	s_waitcnt vmcnt(25)
	v_lshlrev_b32_e32 v41, 16, v77
	v_mad_i64_i32 v[74:75], s[0:1], v42, s53, v[72:73]
	v_mad_i64_i32 v[76:77], s[0:1], v44, s53, v[72:73]
	v_mad_i64_i32 v[72:73], s[0:1], v46, s53, v[72:73]
	s_waitcnt vmcnt(22)
	v_readlane_b32 s0, v18, 0
	global_load_ushort v64, v[74:75], off
	global_load_ushort v59, v[76:77], off
	global_load_ushort v60, v[72:73], off
	v_fma_f32 v71, s0, v51, v53
	v_readlane_b32 s0, v19, 0
	v_lshlrev_b32_e32 v39, 16, v78
	v_mul_f32_e32 v34, 0x3db504f3, v34
	v_fmac_f32_e32 v71, s0, v50
	v_readlane_b32 s0, v20, 0
	v_mul_f32_e32 v33, 0x3db504f3, v33
	v_mul_f32_e32 v32, 0x3db504f3, v32
	s_waitcnt vmcnt(24)
	v_fmac_f32_e32 v71, s0, v70
	v_readlane_b32 s0, v21, 0
	v_mul_f32_e32 v31, 0x3db504f3, v31
	s_waitcnt vmcnt(11)
	v_lshlrev_b32_e32 v46, 16, v38
	v_fmac_f32_e32 v71, s0, v49
	v_readlane_b32 s0, v18, 1
	s_waitcnt vmcnt(10)
	v_lshlrev_b32_e32 v44, 16, v79
	s_waitcnt vmcnt(8)
	v_lshlrev_b32_e32 v40, 16, v40
	v_fmac_f32_e32 v71, s0, v68
	v_readlane_b32 s0, v19, 1
	s_waitcnt vmcnt(1)
	v_lshlrev_b32_e32 v59, 16, v59
	v_fmac_f32_e32 v71, s0, v65
	v_readlane_b32 s0, v20, 1
	s_waitcnt vmcnt(0)
	v_lshlrev_b32_e32 v60, 16, v60
	v_fmac_f32_e32 v71, s0, v69
	v_readlane_b32 s0, v21, 1
	s_nop 1
	v_fmac_f32_e32 v71, s0, v66
	v_readlane_b32 s0, v18, 2
	s_nop 1
	v_fmac_f32_e32 v71, s0, v67
	v_readlane_b32 s0, v19, 2
	s_nop 1
	v_fmac_f32_e32 v71, s0, v62
	v_readlane_b32 s0, v20, 2
	s_nop 1
	v_fmac_f32_e32 v71, s0, v61
	v_readlane_b32 s0, v21, 2
	s_nop 1
	v_fmac_f32_e32 v71, s0, v63
	v_readlane_b32 s0, v18, 3
	s_nop 1
	v_fmac_f32_e32 v71, s0, v58
	v_readlane_b32 s0, v19, 3
	s_nop 1
	v_fmac_f32_e32 v71, s0, v56
	v_readlane_b32 s0, v20, 3
	s_nop 1
	v_fmac_f32_e32 v71, s0, v57
	v_readlane_b32 s0, v21, 3
	s_nop 1
	v_fmac_f32_e32 v71, s0, v55
	v_readlane_b32 s0, v18, 4
	v_mul_f32_e64 v42, |v71|, s60
	v_exp_f32_e32 v72, v42
	v_fma_f32 v74, s0, v51, v53
	v_readlane_b32 s0, v19, 4
	v_min_f32_e32 v71, 0, v71
	v_add_f32_e32 v38, 1.0, v72
	v_fmac_f32_e32 v74, s0, v50
	v_readlane_b32 s0, v20, 4
	v_cmp_gt_f32_e32 vcc, s61, v38
	v_lshlrev_b32_e32 v42, 16, v80
	v_fmac_f32_e32 v74, s0, v70
	v_readlane_b32 s0, v21, 4
	v_cndmask_b32_e64 v72, 0, 32, vcc
	v_ldexp_f32 v38, v38, v72
	v_fmac_f32_e32 v74, s0, v49
	v_readlane_b32 s0, v18, 5
	v_log_f32_e32 v72, v38
	v_lshlrev_b32_e32 v38, 16, v81
	v_fmac_f32_e32 v74, s0, v68
	v_readlane_b32 s0, v19, 5
	v_mul_f32_e32 v73, 0x3f317217, v72
	v_fma_f32 v73, v72, s62, -v73
	v_fmac_f32_e32 v74, s0, v65
	v_readlane_b32 s0, v20, 5
	v_fmac_f32_e32 v73, 0x3377d1cf, v72
	v_fmac_f32_e32 v73, 0x3f317217, v72
	v_fmac_f32_e32 v74, s0, v69
	v_readlane_b32 s0, v21, 5
	s_nop 1
	v_fmac_f32_e32 v74, s0, v66
	v_readlane_b32 s0, v18, 6
	s_nop 1
	v_fmac_f32_e32 v74, s0, v67
	v_readlane_b32 s0, v19, 6
	s_nop 1
	v_fmac_f32_e32 v74, s0, v62
	v_readlane_b32 s0, v20, 6
	s_nop 1
	v_fmac_f32_e32 v74, s0, v61
	v_readlane_b32 s0, v21, 6
	s_nop 1
	v_fmac_f32_e32 v74, s0, v63
	v_readlane_b32 s0, v18, 7
	s_nop 1
	v_fmac_f32_e32 v74, s0, v58
	v_readlane_b32 s0, v19, 7
	s_nop 1
	v_fmac_f32_e32 v74, s0, v56
	v_readlane_b32 s0, v20, 7
	s_nop 1
	v_fmac_f32_e32 v74, s0, v57
	v_readlane_b32 s0, v21, 7
	s_nop 1
	v_fmac_f32_e32 v74, s0, v55
	v_mul_f32_e64 v75, |v74|, s60
	v_exp_f32_e32 v75, v75
	v_cmp_lt_f32_e64 s[0:1], |v72|, s63
	s_nop 1
	v_cndmask_b32_e64 v72, v72, v73, s[0:1]
	v_cndmask_b32_e32 v73, 0, v195, vcc
	v_sub_f32_e32 v72, v72, v73
	v_add_f32_e32 v73, 1.0, v75
	v_cmp_gt_f32_e32 vcc, s61, v73
	v_readlane_b32 s0, v18, 8
	v_sub_f32_e32 v71, v71, v72
	v_cndmask_b32_e64 v75, 0, 32, vcc
	v_ldexp_f32 v73, v73, v75
	v_fma_f32 v75, s0, v51, v53
	v_readlane_b32 s0, v19, 8
	v_log_f32_e32 v73, v73
	v_min_f32_e32 v72, 0, v74
	v_fmac_f32_e32 v75, s0, v50
	v_readlane_b32 s0, v20, 8
	v_mul_f32_e32 v74, 0x3f317217, v73
	v_fma_f32 v74, v73, s62, -v74
	v_fmac_f32_e32 v75, s0, v70
	v_readlane_b32 s0, v21, 8
	v_fmac_f32_e32 v74, 0x3377d1cf, v73
	v_fmac_f32_e32 v74, 0x3f317217, v73
	v_fmac_f32_e32 v75, s0, v49
	v_readlane_b32 s0, v18, 9
	v_fma_f32 v71, v71, s64, 0
	s_nop 0
	v_fmac_f32_e32 v75, s0, v68
	v_readlane_b32 s0, v19, 9
	s_nop 1
	v_fmac_f32_e32 v75, s0, v65
	v_readlane_b32 s0, v20, 9
	s_nop 1
	v_fmac_f32_e32 v75, s0, v69
	v_readlane_b32 s0, v21, 9
	s_nop 1
	v_fmac_f32_e32 v75, s0, v66
	v_readlane_b32 s0, v18, 10
	s_nop 1
	v_fmac_f32_e32 v75, s0, v67
	v_readlane_b32 s0, v19, 10
	s_nop 1
	v_fmac_f32_e32 v75, s0, v62
	v_readlane_b32 s0, v20, 10
	s_nop 1
	v_fmac_f32_e32 v75, s0, v61
	v_readlane_b32 s0, v21, 10
	s_nop 1
	v_fmac_f32_e32 v75, s0, v63
	v_readlane_b32 s0, v18, 11
	s_nop 1
	v_fmac_f32_e32 v75, s0, v58
	v_readlane_b32 s0, v19, 11
	s_nop 1
	v_fmac_f32_e32 v75, s0, v56
	v_readlane_b32 s0, v20, 11
	s_nop 1
	v_fmac_f32_e32 v75, s0, v57
	v_readlane_b32 s0, v21, 11
	s_nop 1
	v_fmac_f32_e32 v75, s0, v55
	v_mul_f32_e64 v76, |v75|, s60
	v_exp_f32_e32 v76, v76
	v_cmp_lt_f32_e64 s[0:1], |v73|, s63
	s_nop 1
	v_cndmask_b32_e64 v73, v73, v74, s[0:1]
	v_cndmask_b32_e32 v74, 0, v195, vcc
	v_sub_f32_e32 v73, v73, v74
	v_add_f32_e32 v74, 1.0, v76
	v_cmp_gt_f32_e32 vcc, s61, v74
	v_readlane_b32 s0, v18, 12
	v_sub_f32_e32 v72, v72, v73
	v_cndmask_b32_e64 v76, 0, 32, vcc
	v_ldexp_f32 v74, v74, v76
	v_fma_f32 v76, s0, v51, v53
	v_readlane_b32 s0, v19, 12
	v_log_f32_e32 v74, v74
	v_min_f32_e32 v73, 0, v75
	v_fmac_f32_e32 v76, s0, v50
	v_readlane_b32 s0, v20, 12
	v_mul_f32_e32 v75, 0x3f317217, v74
	v_fma_f32 v75, v74, s62, -v75
	v_fmac_f32_e32 v76, s0, v70
	v_readlane_b32 s0, v21, 12
	v_fmac_f32_e32 v75, 0x3377d1cf, v74
	v_fmac_f32_e32 v75, 0x3f317217, v74
	v_fmac_f32_e32 v76, s0, v49
	v_readlane_b32 s0, v18, 13
	v_fmamk_f32 v72, v72, 0x3d800000, v71
	s_nop 0
	v_fmac_f32_e32 v76, s0, v68
	v_readlane_b32 s0, v19, 13
	s_nop 1
	v_fmac_f32_e32 v76, s0, v65
	v_readlane_b32 s0, v20, 13
	s_nop 1
	v_fmac_f32_e32 v76, s0, v69
	v_readlane_b32 s0, v21, 13
	s_nop 1
	v_fmac_f32_e32 v76, s0, v66
	v_readlane_b32 s0, v18, 14
	s_nop 1
	v_fmac_f32_e32 v76, s0, v67
	v_readlane_b32 s0, v19, 14
	s_nop 1
	v_fmac_f32_e32 v76, s0, v62
	v_readlane_b32 s0, v20, 14
	s_nop 1
	v_fmac_f32_e32 v76, s0, v61
	v_readlane_b32 s0, v21, 14
	s_nop 1
	v_fmac_f32_e32 v76, s0, v63
	v_readlane_b32 s0, v18, 15
	s_nop 1
	v_fmac_f32_e32 v76, s0, v58
	v_readlane_b32 s0, v19, 15
	s_nop 1
	v_fmac_f32_e32 v76, s0, v56
	v_readlane_b32 s0, v20, 15
	s_nop 1
	v_fmac_f32_e32 v76, s0, v57
	v_readlane_b32 s0, v21, 15
	s_nop 1
	v_fmac_f32_e32 v76, s0, v55
	v_mul_f32_e64 v77, |v76|, s60
	v_exp_f32_e32 v77, v77
	v_cmp_lt_f32_e64 s[0:1], |v74|, s63
	s_nop 1
	v_cndmask_b32_e64 v74, v74, v75, s[0:1]
	v_cndmask_b32_e32 v75, 0, v195, vcc
	v_sub_f32_e32 v74, v74, v75
	v_add_f32_e32 v75, 1.0, v77
	v_cmp_gt_f32_e32 vcc, s61, v75
	v_readlane_b32 s0, v18, 16
	v_sub_f32_e32 v73, v73, v74
	v_cndmask_b32_e64 v77, 0, 32, vcc
	v_ldexp_f32 v75, v75, v77
	v_fma_f32 v77, s0, v51, v53
	v_readlane_b32 s0, v19, 16
	v_log_f32_e32 v75, v75
	v_min_f32_e32 v74, 0, v76
	v_fmac_f32_e32 v77, s0, v50
	v_readlane_b32 s0, v20, 16
	v_mul_f32_e32 v76, 0x3f317217, v75
	v_fma_f32 v76, v75, s62, -v76
	v_fmac_f32_e32 v77, s0, v70
	v_readlane_b32 s0, v21, 16
	v_fmac_f32_e32 v76, 0x3377d1cf, v75
	v_fmac_f32_e32 v76, 0x3f317217, v75
	v_fmac_f32_e32 v77, s0, v49
	v_readlane_b32 s0, v18, 17
	v_fmamk_f32 v73, v73, 0x3d800000, v72
	s_nop 0
	v_fmac_f32_e32 v77, s0, v68
	v_readlane_b32 s0, v19, 17
	s_nop 1
	v_fmac_f32_e32 v77, s0, v65
	v_readlane_b32 s0, v20, 17
	s_nop 1
	v_fmac_f32_e32 v77, s0, v69
	v_readlane_b32 s0, v21, 17
	s_nop 1
	v_fmac_f32_e32 v77, s0, v66
	v_readlane_b32 s0, v18, 18
	s_nop 1
	v_fmac_f32_e32 v77, s0, v67
	v_readlane_b32 s0, v19, 18
	s_nop 1
	v_fmac_f32_e32 v77, s0, v62
	v_readlane_b32 s0, v20, 18
	s_nop 1
	v_fmac_f32_e32 v77, s0, v61
	v_readlane_b32 s0, v21, 18
	s_nop 1
	v_fmac_f32_e32 v77, s0, v63
	v_readlane_b32 s0, v18, 19
	s_nop 1
	v_fmac_f32_e32 v77, s0, v58
	v_readlane_b32 s0, v19, 19
	s_nop 1
	v_fmac_f32_e32 v77, s0, v56
	v_readlane_b32 s0, v20, 19
	s_nop 1
	v_fmac_f32_e32 v77, s0, v57
	v_readlane_b32 s0, v21, 19
	s_nop 1
	v_fmac_f32_e32 v77, s0, v55
	v_mul_f32_e64 v78, |v77|, s60
	v_exp_f32_e32 v78, v78
	v_cmp_lt_f32_e64 s[0:1], |v75|, s63
	s_nop 1
	v_cndmask_b32_e64 v75, v75, v76, s[0:1]
	v_cndmask_b32_e32 v76, 0, v195, vcc
	v_sub_f32_e32 v75, v75, v76
	v_add_f32_e32 v76, 1.0, v78
	v_cmp_gt_f32_e32 vcc, s61, v76
	v_readlane_b32 s0, v18, 20
	v_sub_f32_e32 v74, v74, v75
	v_cndmask_b32_e64 v78, 0, 32, vcc
	v_ldexp_f32 v76, v76, v78
	v_fma_f32 v78, s0, v51, v53
	v_readlane_b32 s0, v19, 20
	v_log_f32_e32 v76, v76
	v_min_f32_e32 v75, 0, v77
	v_fmac_f32_e32 v78, s0, v50
	v_readlane_b32 s0, v20, 20
	v_mul_f32_e32 v77, 0x3f317217, v76
	v_fma_f32 v77, v76, s62, -v77
	v_fmac_f32_e32 v78, s0, v70
	v_readlane_b32 s0, v21, 20
	v_fmac_f32_e32 v77, 0x3377d1cf, v76
	v_fmac_f32_e32 v77, 0x3f317217, v76
	v_fmac_f32_e32 v78, s0, v49
	v_readlane_b32 s0, v18, 21
	v_fmamk_f32 v74, v74, 0x3d800000, v73
	s_nop 0
	v_fmac_f32_e32 v78, s0, v68
	v_readlane_b32 s0, v19, 21
	s_nop 1
	v_fmac_f32_e32 v78, s0, v65
	v_readlane_b32 s0, v20, 21
	s_nop 1
	v_fmac_f32_e32 v78, s0, v69
	v_readlane_b32 s0, v21, 21
	s_nop 1
	v_fmac_f32_e32 v78, s0, v66
	v_readlane_b32 s0, v18, 22
	s_nop 1
	v_fmac_f32_e32 v78, s0, v67
	v_readlane_b32 s0, v19, 22
	s_nop 1
	v_fmac_f32_e32 v78, s0, v62
	v_readlane_b32 s0, v20, 22
	s_nop 1
	v_fmac_f32_e32 v78, s0, v61
	v_readlane_b32 s0, v21, 22
	s_nop 1
	v_fmac_f32_e32 v78, s0, v63
	v_readlane_b32 s0, v18, 23
	s_nop 1
	v_fmac_f32_e32 v78, s0, v58
	v_readlane_b32 s0, v19, 23
	s_nop 1
	v_fmac_f32_e32 v78, s0, v56
	v_readlane_b32 s0, v20, 23
	s_nop 1
	v_fmac_f32_e32 v78, s0, v57
	v_readlane_b32 s0, v21, 23
	s_nop 1
	v_fmac_f32_e32 v78, s0, v55
	v_mul_f32_e64 v79, |v78|, s60
	v_exp_f32_e32 v79, v79
	v_cmp_lt_f32_e64 s[0:1], |v76|, s63
	s_nop 1
	v_cndmask_b32_e64 v76, v76, v77, s[0:1]
	v_cndmask_b32_e32 v77, 0, v195, vcc
	v_sub_f32_e32 v76, v76, v77
	v_add_f32_e32 v77, 1.0, v79
	v_cmp_gt_f32_e32 vcc, s61, v77
	v_readlane_b32 s0, v18, 24
	v_sub_f32_e32 v75, v75, v76
	v_cndmask_b32_e64 v79, 0, 32, vcc
	v_ldexp_f32 v77, v77, v79
	v_fma_f32 v79, s0, v51, v53
	v_readlane_b32 s0, v19, 24
	v_log_f32_e32 v77, v77
	v_min_f32_e32 v76, 0, v78
	v_fmac_f32_e32 v79, s0, v50
	v_readlane_b32 s0, v20, 24
	v_mul_f32_e32 v78, 0x3f317217, v77
	v_fma_f32 v78, v77, s62, -v78
	v_fmac_f32_e32 v79, s0, v70
	v_readlane_b32 s0, v21, 24
	v_fmac_f32_e32 v78, 0x3377d1cf, v77
	v_fmac_f32_e32 v78, 0x3f317217, v77
	v_fmac_f32_e32 v79, s0, v49
	v_readlane_b32 s0, v18, 25
	v_fmamk_f32 v75, v75, 0x3d800000, v74
	s_nop 0
	v_fmac_f32_e32 v79, s0, v68
	v_readlane_b32 s0, v19, 25
	s_nop 1
	v_fmac_f32_e32 v79, s0, v65
	v_readlane_b32 s0, v20, 25
	s_nop 1
	v_fmac_f32_e32 v79, s0, v69
	v_readlane_b32 s0, v21, 25
	s_nop 1
	v_fmac_f32_e32 v79, s0, v66
	v_readlane_b32 s0, v18, 26
	s_nop 1
	v_fmac_f32_e32 v79, s0, v67
	v_readlane_b32 s0, v19, 26
	s_nop 1
	v_fmac_f32_e32 v79, s0, v62
	v_readlane_b32 s0, v20, 26
	s_nop 1
	v_fmac_f32_e32 v79, s0, v61
	v_readlane_b32 s0, v21, 26
	s_nop 1
	v_fmac_f32_e32 v79, s0, v63
	v_readlane_b32 s0, v18, 27
	s_nop 1
	v_fmac_f32_e32 v79, s0, v58
	v_readlane_b32 s0, v19, 27
	s_nop 1
	v_fmac_f32_e32 v79, s0, v56
	v_readlane_b32 s0, v20, 27
	s_nop 1
	v_fmac_f32_e32 v79, s0, v57
	v_readlane_b32 s0, v21, 27
	s_nop 1
	v_fmac_f32_e32 v79, s0, v55
	v_mul_f32_e64 v80, |v79|, s60
	v_exp_f32_e32 v80, v80
	v_cmp_lt_f32_e64 s[0:1], |v77|, s63
	s_nop 1
	v_cndmask_b32_e64 v77, v77, v78, s[0:1]
	v_cndmask_b32_e32 v78, 0, v195, vcc
	v_sub_f32_e32 v77, v77, v78
	v_add_f32_e32 v78, 1.0, v80
	v_cmp_gt_f32_e32 vcc, s61, v78
	v_readlane_b32 s0, v18, 28
	v_sub_f32_e32 v76, v76, v77
	v_cndmask_b32_e64 v80, 0, 32, vcc
	v_ldexp_f32 v78, v78, v80
	v_fma_f32 v80, s0, v51, v53
	v_readlane_b32 s0, v19, 28
	v_log_f32_e32 v78, v78
	v_min_f32_e32 v77, 0, v79
	v_fmac_f32_e32 v80, s0, v50
	v_readlane_b32 s0, v20, 28
	v_mul_f32_e32 v79, 0x3f317217, v78
	v_fma_f32 v79, v78, s62, -v79
	v_fmac_f32_e32 v80, s0, v70
	v_readlane_b32 s0, v21, 28
	v_fmac_f32_e32 v79, 0x3377d1cf, v78
	v_fmac_f32_e32 v79, 0x3f317217, v78
	v_fmac_f32_e32 v80, s0, v49
	v_readlane_b32 s0, v18, 29
	v_fmamk_f32 v76, v76, 0x3d800000, v75
	s_nop 0
	v_fmac_f32_e32 v80, s0, v68
	v_readlane_b32 s0, v19, 29
	s_nop 1
	v_fmac_f32_e32 v80, s0, v65
	v_readlane_b32 s0, v20, 29
	s_nop 1
	v_fmac_f32_e32 v80, s0, v69
	v_readlane_b32 s0, v21, 29
	s_nop 1
	v_fmac_f32_e32 v80, s0, v66
	v_readlane_b32 s0, v18, 30
	s_nop 1
	v_fmac_f32_e32 v80, s0, v67
	v_readlane_b32 s0, v19, 30
	s_nop 1
	v_fmac_f32_e32 v80, s0, v62
	v_readlane_b32 s0, v20, 30
	s_nop 1
	v_fmac_f32_e32 v80, s0, v61
	v_readlane_b32 s0, v21, 30
	s_nop 1
	v_fmac_f32_e32 v80, s0, v63
	v_readlane_b32 s0, v18, 31
	s_nop 1
	v_fmac_f32_e32 v80, s0, v58
	v_readlane_b32 s0, v19, 31
	s_nop 1
	v_fmac_f32_e32 v80, s0, v56
	v_readlane_b32 s0, v20, 31
	s_nop 1
	v_fmac_f32_e32 v80, s0, v57
	v_readlane_b32 s0, v21, 31
	s_nop 1
	v_fmac_f32_e32 v80, s0, v55
	v_mul_f32_e64 v81, |v80|, s60
	v_exp_f32_e32 v81, v81
	v_cmp_lt_f32_e64 s[0:1], |v78|, s63
	s_nop 1
	v_cndmask_b32_e64 v78, v78, v79, s[0:1]
	v_cndmask_b32_e32 v79, 0, v195, vcc
	v_sub_f32_e32 v78, v78, v79
	v_add_f32_e32 v79, 1.0, v81
	v_cmp_gt_f32_e32 vcc, s61, v79
	v_readlane_b32 s0, v18, 32
	v_sub_f32_e32 v77, v77, v78
	v_cndmask_b32_e64 v81, 0, 32, vcc
	v_ldexp_f32 v79, v79, v81
	v_fma_f32 v81, s0, v51, v53
	v_readlane_b32 s0, v19, 32
	v_log_f32_e32 v79, v79
	v_min_f32_e32 v78, 0, v80
	v_fmac_f32_e32 v81, s0, v50
	v_readlane_b32 s0, v20, 32
	v_mul_f32_e32 v80, 0x3f317217, v79
	v_fma_f32 v80, v79, s62, -v80
	v_fmac_f32_e32 v81, s0, v70
	v_readlane_b32 s0, v21, 32
	v_fmac_f32_e32 v80, 0x3377d1cf, v79
	v_fmac_f32_e32 v80, 0x3f317217, v79
	v_fmac_f32_e32 v81, s0, v49
	v_readlane_b32 s0, v18, 33
	v_fmamk_f32 v77, v77, 0x3d800000, v76
	s_nop 0
	v_fmac_f32_e32 v81, s0, v68
	v_readlane_b32 s0, v19, 33
	s_nop 1
	v_fmac_f32_e32 v81, s0, v65
	v_readlane_b32 s0, v20, 33
	s_nop 1
	v_fmac_f32_e32 v81, s0, v69
	v_readlane_b32 s0, v21, 33
	s_nop 1
	v_fmac_f32_e32 v81, s0, v66
	v_readlane_b32 s0, v18, 34
	s_nop 1
	v_fmac_f32_e32 v81, s0, v67
	v_readlane_b32 s0, v19, 34
	s_nop 1
	v_fmac_f32_e32 v81, s0, v62
	v_readlane_b32 s0, v20, 34
	s_nop 1
	v_fmac_f32_e32 v81, s0, v61
	v_readlane_b32 s0, v21, 34
	s_nop 1
	v_fmac_f32_e32 v81, s0, v63
	v_readlane_b32 s0, v18, 35
	s_nop 1
	v_fmac_f32_e32 v81, s0, v58
	v_readlane_b32 s0, v19, 35
	s_nop 1
	v_fmac_f32_e32 v81, s0, v56
	v_readlane_b32 s0, v20, 35
	s_nop 1
	v_fmac_f32_e32 v81, s0, v57
	v_readlane_b32 s0, v21, 35
	s_nop 1
	v_fmac_f32_e32 v81, s0, v55
	v_mul_f32_e64 v82, |v81|, s60
	v_exp_f32_e32 v82, v82
	v_cmp_lt_f32_e64 s[0:1], |v79|, s63
	s_nop 1
	v_cndmask_b32_e64 v79, v79, v80, s[0:1]
	v_cndmask_b32_e32 v80, 0, v195, vcc
	v_sub_f32_e32 v79, v79, v80
	v_add_f32_e32 v80, 1.0, v82
	v_cmp_gt_f32_e32 vcc, s61, v80
	v_readlane_b32 s0, v18, 36
	v_sub_f32_e32 v78, v78, v79
	v_cndmask_b32_e64 v82, 0, 32, vcc
	v_ldexp_f32 v80, v80, v82
	v_fma_f32 v82, s0, v51, v53
	v_readlane_b32 s0, v19, 36
	v_log_f32_e32 v80, v80
	v_min_f32_e32 v79, 0, v81
	v_fmac_f32_e32 v82, s0, v50
	v_readlane_b32 s0, v20, 36
	v_mul_f32_e32 v81, 0x3f317217, v80
	v_fma_f32 v81, v80, s62, -v81
	v_fmac_f32_e32 v82, s0, v70
	v_readlane_b32 s0, v21, 36
	v_fmac_f32_e32 v81, 0x3377d1cf, v80
	v_fmac_f32_e32 v81, 0x3f317217, v80
	v_fmac_f32_e32 v82, s0, v49
	v_readlane_b32 s0, v18, 37
	v_fmamk_f32 v78, v78, 0x3d800000, v77
	s_nop 0
	v_fmac_f32_e32 v82, s0, v68
	v_readlane_b32 s0, v19, 37
	s_nop 1
	v_fmac_f32_e32 v82, s0, v65
	v_readlane_b32 s0, v20, 37
	s_nop 1
	v_fmac_f32_e32 v82, s0, v69
	v_readlane_b32 s0, v21, 37
	s_nop 1
	v_fmac_f32_e32 v82, s0, v66
	v_readlane_b32 s0, v18, 38
	s_nop 1
	v_fmac_f32_e32 v82, s0, v67
	v_readlane_b32 s0, v19, 38
	s_nop 1
	v_fmac_f32_e32 v82, s0, v62
	v_readlane_b32 s0, v20, 38
	s_nop 1
	v_fmac_f32_e32 v82, s0, v61
	v_readlane_b32 s0, v21, 38
	s_nop 1
	v_fmac_f32_e32 v82, s0, v63
	v_readlane_b32 s0, v18, 39
	s_nop 1
	v_fmac_f32_e32 v82, s0, v58
	v_readlane_b32 s0, v19, 39
	s_nop 1
	v_fmac_f32_e32 v82, s0, v56
	v_readlane_b32 s0, v20, 39
	s_nop 1
	v_fmac_f32_e32 v82, s0, v57
	v_readlane_b32 s0, v21, 39
	s_nop 1
	v_fmac_f32_e32 v82, s0, v55
	v_mul_f32_e64 v83, |v82|, s60
	v_exp_f32_e32 v83, v83
	v_cmp_lt_f32_e64 s[0:1], |v80|, s63
	s_nop 1
	v_cndmask_b32_e64 v80, v80, v81, s[0:1]
	v_cndmask_b32_e32 v81, 0, v195, vcc
	v_sub_f32_e32 v80, v80, v81
	v_add_f32_e32 v81, 1.0, v83
	v_cmp_gt_f32_e32 vcc, s61, v81
	v_readlane_b32 s0, v18, 40
	v_sub_f32_e32 v79, v79, v80
	v_cndmask_b32_e64 v83, 0, 32, vcc
	v_ldexp_f32 v81, v81, v83
	v_fma_f32 v83, s0, v51, v53
	v_readlane_b32 s0, v19, 40
	v_log_f32_e32 v81, v81
	v_min_f32_e32 v80, 0, v82
	v_fmac_f32_e32 v83, s0, v50
	v_readlane_b32 s0, v20, 40
	v_mul_f32_e32 v82, 0x3f317217, v81
	v_fma_f32 v82, v81, s62, -v82
	v_fmac_f32_e32 v83, s0, v70
	v_readlane_b32 s0, v21, 40
	v_fmac_f32_e32 v82, 0x3377d1cf, v81
	v_fmac_f32_e32 v82, 0x3f317217, v81
	v_fmac_f32_e32 v83, s0, v49
	v_readlane_b32 s0, v18, 41
	v_fmamk_f32 v79, v79, 0x3d800000, v78
	s_nop 0
	v_fmac_f32_e32 v83, s0, v68
	v_readlane_b32 s0, v19, 41
	s_nop 1
	v_fmac_f32_e32 v83, s0, v65
	v_readlane_b32 s0, v20, 41
	s_nop 1
	v_fmac_f32_e32 v83, s0, v69
	v_readlane_b32 s0, v21, 41
	s_nop 1
	v_fmac_f32_e32 v83, s0, v66
	v_readlane_b32 s0, v18, 42
	s_nop 1
	v_fmac_f32_e32 v83, s0, v67
	v_readlane_b32 s0, v19, 42
	s_nop 1
	v_fmac_f32_e32 v83, s0, v62
	v_readlane_b32 s0, v20, 42
	s_nop 1
	v_fmac_f32_e32 v83, s0, v61
	v_readlane_b32 s0, v21, 42
	s_nop 1
	v_fmac_f32_e32 v83, s0, v63
	v_readlane_b32 s0, v18, 43
	s_nop 1
	v_fmac_f32_e32 v83, s0, v58
	v_readlane_b32 s0, v19, 43
	s_nop 1
	v_fmac_f32_e32 v83, s0, v56
	v_readlane_b32 s0, v20, 43
	s_nop 1
	v_fmac_f32_e32 v83, s0, v57
	v_readlane_b32 s0, v21, 43
	s_nop 1
	v_fmac_f32_e32 v83, s0, v55
	v_mul_f32_e64 v84, |v83|, s60
	v_exp_f32_e32 v84, v84
	v_cmp_lt_f32_e64 s[0:1], |v81|, s63
	s_nop 1
	v_cndmask_b32_e64 v81, v81, v82, s[0:1]
	v_cndmask_b32_e32 v82, 0, v195, vcc
	v_sub_f32_e32 v81, v81, v82
	v_add_f32_e32 v82, 1.0, v84
	v_cmp_gt_f32_e32 vcc, s61, v82
	v_readlane_b32 s0, v18, 44
	v_sub_f32_e32 v80, v80, v81
	v_cndmask_b32_e64 v84, 0, 32, vcc
	v_ldexp_f32 v82, v82, v84
	v_fma_f32 v84, s0, v51, v53
	v_readlane_b32 s0, v19, 44
	v_log_f32_e32 v82, v82
	v_min_f32_e32 v81, 0, v83
	v_fmac_f32_e32 v84, s0, v50
	v_readlane_b32 s0, v20, 44
	v_mul_f32_e32 v83, 0x3f317217, v82
	v_fma_f32 v83, v82, s62, -v83
	v_fmac_f32_e32 v84, s0, v70
	v_readlane_b32 s0, v21, 44
	v_fmac_f32_e32 v83, 0x3377d1cf, v82
	v_fmac_f32_e32 v83, 0x3f317217, v82
	v_fmac_f32_e32 v84, s0, v49
	v_readlane_b32 s0, v18, 45
	v_fmamk_f32 v80, v80, 0x3d800000, v79
	s_nop 0
	v_fmac_f32_e32 v84, s0, v68
	v_readlane_b32 s0, v19, 45
	s_nop 1
	v_fmac_f32_e32 v84, s0, v65
	v_readlane_b32 s0, v20, 45
	s_nop 1
	v_fmac_f32_e32 v84, s0, v69
	v_readlane_b32 s0, v21, 45
	s_nop 1
	v_fmac_f32_e32 v84, s0, v66
	v_readlane_b32 s0, v18, 46
	s_nop 1
	v_fmac_f32_e32 v84, s0, v67
	v_readlane_b32 s0, v19, 46
	s_nop 1
	v_fmac_f32_e32 v84, s0, v62
	v_readlane_b32 s0, v20, 46
	s_nop 1
	v_fmac_f32_e32 v84, s0, v61
	v_readlane_b32 s0, v21, 46
	s_nop 1
	v_fmac_f32_e32 v84, s0, v63
	v_readlane_b32 s0, v18, 47
	s_nop 1
	v_fmac_f32_e32 v84, s0, v58
	v_readlane_b32 s0, v19, 47
	s_nop 1
	v_fmac_f32_e32 v84, s0, v56
	v_readlane_b32 s0, v20, 47
	s_nop 1
	v_fmac_f32_e32 v84, s0, v57
	v_readlane_b32 s0, v21, 47
	s_nop 1
	v_fmac_f32_e32 v84, s0, v55
	v_mul_f32_e64 v85, |v84|, s60
	v_exp_f32_e32 v85, v85
	v_cmp_lt_f32_e64 s[0:1], |v82|, s63
	s_nop 1
	v_cndmask_b32_e64 v82, v82, v83, s[0:1]
	v_cndmask_b32_e32 v83, 0, v195, vcc
	v_sub_f32_e32 v82, v82, v83
	v_add_f32_e32 v83, 1.0, v85
	v_cmp_gt_f32_e32 vcc, s61, v83
	v_readlane_b32 s0, v18, 48
	v_sub_f32_e32 v81, v81, v82
	v_cndmask_b32_e64 v85, 0, 32, vcc
	v_ldexp_f32 v83, v83, v85
	v_fma_f32 v85, s0, v51, v53
	v_readlane_b32 s0, v19, 48
	v_log_f32_e32 v83, v83
	v_min_f32_e32 v82, 0, v84
	v_fmac_f32_e32 v85, s0, v50
	v_readlane_b32 s0, v20, 48
	v_mul_f32_e32 v84, 0x3f317217, v83
	v_fma_f32 v84, v83, s62, -v84
	v_fmac_f32_e32 v85, s0, v70
	v_readlane_b32 s0, v21, 48
	v_fmac_f32_e32 v84, 0x3377d1cf, v83
	v_fmac_f32_e32 v84, 0x3f317217, v83
	v_fmac_f32_e32 v85, s0, v49
	v_readlane_b32 s0, v18, 49
	v_fmamk_f32 v81, v81, 0x3d800000, v80
	s_nop 0
	v_fmac_f32_e32 v85, s0, v68
	v_readlane_b32 s0, v19, 49
	s_nop 1
	v_fmac_f32_e32 v85, s0, v65
	v_readlane_b32 s0, v20, 49
	s_nop 1
	v_fmac_f32_e32 v85, s0, v69
	v_readlane_b32 s0, v21, 49
	s_nop 1
	v_fmac_f32_e32 v85, s0, v66
	v_readlane_b32 s0, v18, 50
	s_nop 1
	v_fmac_f32_e32 v85, s0, v67
	v_readlane_b32 s0, v19, 50
	s_nop 1
	v_fmac_f32_e32 v85, s0, v62
	v_readlane_b32 s0, v20, 50
	s_nop 1
	v_fmac_f32_e32 v85, s0, v61
	v_readlane_b32 s0, v21, 50
	s_nop 1
	v_fmac_f32_e32 v85, s0, v63
	v_readlane_b32 s0, v18, 51
	s_nop 1
	v_fmac_f32_e32 v85, s0, v58
	v_readlane_b32 s0, v19, 51
	s_nop 1
	v_fmac_f32_e32 v85, s0, v56
	v_readlane_b32 s0, v20, 51
	s_nop 1
	v_fmac_f32_e32 v85, s0, v57
	v_readlane_b32 s0, v21, 51
	s_nop 1
	v_fmac_f32_e32 v85, s0, v55
	v_mul_f32_e64 v86, |v85|, s60
	v_exp_f32_e32 v86, v86
	v_cmp_lt_f32_e64 s[0:1], |v83|, s63
	s_nop 1
	v_cndmask_b32_e64 v83, v83, v84, s[0:1]
	v_cndmask_b32_e32 v84, 0, v195, vcc
	v_sub_f32_e32 v83, v83, v84
	v_add_f32_e32 v84, 1.0, v86
	v_cmp_gt_f32_e32 vcc, s61, v84
	v_readlane_b32 s0, v18, 52
	v_sub_f32_e32 v82, v82, v83
	v_cndmask_b32_e64 v86, 0, 32, vcc
	v_ldexp_f32 v84, v84, v86
	v_fma_f32 v86, s0, v51, v53
	v_readlane_b32 s0, v19, 52
	v_log_f32_e32 v84, v84
	v_min_f32_e32 v83, 0, v85
	v_fmac_f32_e32 v86, s0, v50
	v_readlane_b32 s0, v20, 52
	v_mul_f32_e32 v85, 0x3f317217, v84
	v_fma_f32 v85, v84, s62, -v85
	v_fmac_f32_e32 v86, s0, v70
	v_readlane_b32 s0, v21, 52
	v_fmac_f32_e32 v85, 0x3377d1cf, v84
	v_fmac_f32_e32 v85, 0x3f317217, v84
	v_fmac_f32_e32 v86, s0, v49
	v_readlane_b32 s0, v18, 53
	v_fmamk_f32 v82, v82, 0x3d800000, v81
	s_nop 0
	v_fmac_f32_e32 v86, s0, v68
	v_readlane_b32 s0, v19, 53
	s_nop 1
	v_fmac_f32_e32 v86, s0, v65
	v_readlane_b32 s0, v20, 53
	s_nop 1
	v_fmac_f32_e32 v86, s0, v69
	v_readlane_b32 s0, v21, 53
	s_nop 1
	v_fmac_f32_e32 v86, s0, v66
	v_readlane_b32 s0, v18, 54
	s_nop 1
	v_fmac_f32_e32 v86, s0, v67
	v_readlane_b32 s0, v19, 54
	s_nop 1
	v_fmac_f32_e32 v86, s0, v62
	v_readlane_b32 s0, v20, 54
	s_nop 1
	v_fmac_f32_e32 v86, s0, v61
	v_readlane_b32 s0, v21, 54
	s_nop 1
	v_fmac_f32_e32 v86, s0, v63
	v_readlane_b32 s0, v18, 55
	s_nop 1
	v_fmac_f32_e32 v86, s0, v58
	v_readlane_b32 s0, v19, 55
	s_nop 1
	v_fmac_f32_e32 v86, s0, v56
	v_readlane_b32 s0, v20, 55
	s_nop 1
	v_fmac_f32_e32 v86, s0, v57
	v_readlane_b32 s0, v21, 55
	s_nop 1
	v_fmac_f32_e32 v86, s0, v55
	v_mul_f32_e64 v87, |v86|, s60
	v_exp_f32_e32 v87, v87
	v_cmp_lt_f32_e64 s[0:1], |v84|, s63
	s_nop 1
	v_cndmask_b32_e64 v84, v84, v85, s[0:1]
	v_cndmask_b32_e32 v85, 0, v195, vcc
	v_sub_f32_e32 v84, v84, v85
	v_add_f32_e32 v85, 1.0, v87
	v_cmp_gt_f32_e32 vcc, s61, v85
	v_readlane_b32 s0, v18, 56
	v_sub_f32_e32 v83, v83, v84
	v_cndmask_b32_e64 v87, 0, 32, vcc
	v_ldexp_f32 v85, v85, v87
	v_fma_f32 v87, s0, v51, v53
	v_readlane_b32 s0, v19, 56
	v_log_f32_e32 v85, v85
	v_min_f32_e32 v84, 0, v86
	v_fmac_f32_e32 v87, s0, v50
	v_readlane_b32 s0, v20, 56
	v_mul_f32_e32 v86, 0x3f317217, v85
	v_fma_f32 v86, v85, s62, -v86
	v_fmac_f32_e32 v87, s0, v70
	v_readlane_b32 s0, v21, 56
	v_fmac_f32_e32 v86, 0x3377d1cf, v85
	v_fmac_f32_e32 v86, 0x3f317217, v85
	v_fmac_f32_e32 v87, s0, v49
	v_readlane_b32 s0, v18, 57
	v_fmamk_f32 v83, v83, 0x3d800000, v82
	s_nop 0
	v_fmac_f32_e32 v87, s0, v68
	v_readlane_b32 s0, v19, 57
	s_nop 1
	v_fmac_f32_e32 v87, s0, v65
	v_readlane_b32 s0, v20, 57
	s_nop 1
	v_fmac_f32_e32 v87, s0, v69
	v_readlane_b32 s0, v21, 57
	s_nop 1
	v_fmac_f32_e32 v87, s0, v66
	v_readlane_b32 s0, v18, 58
	s_nop 1
	v_fmac_f32_e32 v87, s0, v67
	v_readlane_b32 s0, v19, 58
	s_nop 1
	v_fmac_f32_e32 v87, s0, v62
	v_readlane_b32 s0, v20, 58
	s_nop 1
	v_fmac_f32_e32 v87, s0, v61
	v_readlane_b32 s0, v21, 58
	s_nop 1
	v_fmac_f32_e32 v87, s0, v63
	v_readlane_b32 s0, v18, 59
	s_nop 1
	v_fmac_f32_e32 v87, s0, v58
	v_readlane_b32 s0, v19, 59
	s_nop 1
	v_fmac_f32_e32 v87, s0, v56
	v_readlane_b32 s0, v20, 59
	s_nop 1
	v_fmac_f32_e32 v87, s0, v57
	v_readlane_b32 s0, v21, 59
	s_nop 1
	v_fmac_f32_e32 v87, s0, v55
	v_cmp_lt_f32_e64 s[0:1], |v85|, s63
	v_mul_f32_e64 v88, |v87|, s60
	v_exp_f32_e32 v88, v88
	v_cndmask_b32_e64 v85, v85, v86, s[0:1]
	v_readlane_b32 s0, v18, 60
	v_cndmask_b32_e32 v86, 0, v195, vcc
	v_sub_f32_e32 v85, v85, v86
	v_fmac_f32_e32 v53, s0, v51
	v_readlane_b32 s0, v19, 60
	v_add_f32_e32 v86, 1.0, v88
	v_cmp_gt_f32_e32 vcc, s61, v86
	v_fmac_f32_e32 v53, s0, v50
	v_readlane_b32 s0, v20, 60
	v_cndmask_b32_e64 v88, 0, 32, vcc
	v_ldexp_f32 v86, v86, v88
	v_fmac_f32_e32 v53, s0, v70
	v_readlane_b32 s0, v21, 60
	v_log_f32_e32 v86, v86
	v_sub_f32_e32 v84, v84, v85
	v_fmac_f32_e32 v53, s0, v49
	v_readlane_b32 s0, v18, 61
	v_min_f32_e32 v85, 0, v87
	v_mul_f32_e32 v87, 0x3f317217, v86
	v_fmac_f32_e32 v53, s0, v68
	v_readlane_b32 s0, v19, 61
	v_fma_f32 v87, v86, s62, -v87
	v_fmac_f32_e32 v87, 0x3377d1cf, v86
	v_fmac_f32_e32 v53, s0, v65
	v_readlane_b32 s0, v20, 61
	v_fmac_f32_e32 v87, 0x3f317217, v86
	v_fmamk_f32 v84, v84, 0x3d800000, v83
	v_fmac_f32_e32 v53, s0, v69
	v_readlane_b32 s0, v21, 61
	s_nop 1
	v_fmac_f32_e32 v53, s0, v66
	v_readlane_b32 s0, v18, 62
	s_nop 1
	v_fmac_f32_e32 v53, s0, v67
	v_readlane_b32 s0, v19, 62
	s_nop 1
	v_fmac_f32_e32 v53, s0, v62
	v_readlane_b32 s0, v20, 62
	s_nop 1
	v_fmac_f32_e32 v53, s0, v61
	v_readlane_b32 s0, v21, 62
	s_nop 1
	v_fmac_f32_e32 v53, s0, v63
	v_readlane_b32 s0, v18, 63
	s_nop 1
	v_fmac_f32_e32 v53, s0, v58
	v_readlane_b32 s0, v19, 63
	v_lshlrev_b32_e32 v58, 16, v64
	s_nop 0
	v_fmac_f32_e32 v53, s0, v56
	v_readlane_b32 s0, v20, 63
	v_cndmask_b32_e32 v20, 0, v195, vcc
	s_nop 0
	v_fmac_f32_e32 v53, s0, v57
	v_readlane_b32 s0, v21, 63
	s_nop 1
	v_fmac_f32_e32 v53, s0, v55
	v_mul_f32_e64 v18, |v53|, s60
	v_exp_f32_e32 v18, v18
	v_cmp_lt_f32_e64 s[0:1], |v86|, s63
	v_add_f32_e32 v18, 1.0, v18
	s_nop 0
	v_cndmask_b32_e64 v19, v86, v87, s[0:1]
	v_cmp_gt_f32_e32 vcc, s61, v18
	v_sub_f32_e32 v19, v19, v20
	v_sub_f32_e32 v19, v85, v19
	v_cndmask_b32_e64 v20, 0, 32, vcc
	v_ldexp_f32 v18, v18, v20
	v_log_f32_e32 v18, v18
	v_fmamk_f32 v55, v19, 0x3d800000, v84
	v_min_f32_e32 v19, 0, v53
	v_mul_f32_e32 v20, 0x3f317217, v18
	v_fma_f32 v20, v18, s62, -v20
	v_fmac_f32_e32 v20, 0x3377d1cf, v18
	v_fmac_f32_e32 v20, 0x3f317217, v18
	v_cmp_lt_f32_e64 s[0:1], |v18|, s63
	s_nop 1
	v_cndmask_b32_e64 v18, v18, v20, s[0:1]
	v_cndmask_b32_e32 v20, 0, v195, vcc
	v_sub_f32_e32 v18, v18, v20
	v_sub_f32_e32 v18, v19, v18
	v_fmamk_f32 v53, v18, 0x3d800000, v55
	ds_write_b32 v141, v53
	s_waitcnt lgkmcnt(0)
	s_barrier
	ds_read2st64_b32 v[18:19], v143 offset1:2
	ds_read2st64_b32 v[50:51], v143 offset0:4 offset1:6
	v_or_b32_e32 v20, s21, v149
	s_waitcnt lgkmcnt(1)
	v_add_f32_e32 v49, 0, v18
	v_add_f32_e32 v21, v49, v19
	s_waitcnt lgkmcnt(0)
	v_add_f32_e32 v18, v21, v50
	v_add_f32_e32 v19, v18, v51
	v_mov_b64_e32 v[50:51], s[26:27]
	v_mad_i64_i32 v[174:175], s[0:1], v20, s53, v[50:51]
	s_lshr_b32 s0, s69, 1
	v_lshl_add_u64 v[50:51], s[24:25], 1, v[174:175]
	s_and_b32 s70, s0, 0x7fffff80
	v_lshl_add_u64 v[50:51], v[50:51], 0, v[156:157]
	s_lshl_b32 s0, s70, 1
	s_mov_b32 s1, s25
	v_lshl_add_u64 v[50:51], v[50:51], 0, s[0:1]
	v_lshl_add_u64 v[56:57], v[50:51], 0, s[30:31]
	v_add_co_u32_e32 v50, vcc, s54, v50
	s_nop 1
	v_addc_co_u32_e32 v51, vcc, 0, v51, vcc
	v_cmp_eq_u32_e32 vcc, 1, v1
	s_mul_hi_u32 s99, s67, 0xaaaaaaab
	v_and_b32_e32 v86, 15, v0
	v_bfe_u32 v87, v0, 4, 2
	v_lshrrev_b32_e32 v88, 6, v0
	s_lshr_b32 s99, s99, 3
	s_mul_i32 s100, s99, 12
	s_sub_u32 s100, s67, s100
	s_lshl_b32 s101, s99, 2
	s_add_i32 s101, s101, s100
	s_add_i32 s101, s101, -8
	s_lshl_b32 s101, s101, 16
	s_add_u32 s0, s44, s101
	s_addc_u32 s1, s45, 0
	v_lshlrev_b32_e32 v89, 8, v86
	v_lshl_add_u32 v89, v87, 4, v89
	v_lshl_add_u32 v89, v88, 13, v89
	global_load_dwordx4 v[208:211], v89, s[0:1]
	global_load_dwordx4 v[212:215], v89, s[0:1] offset:64
	global_load_dwordx4 v[216:219], v89, s[0:1] offset:128
	global_load_dwordx4 v[220:223], v89, s[0:1] offset:192
	v_add_u32_e32 v90, 0x1000, v89
	global_load_dwordx4 v[224:227], v90, s[0:1]
	global_load_dwordx4 v[228:231], v90, s[0:1] offset:64
	global_load_dwordx4 v[232:235], v90, s[0:1] offset:128
	global_load_dwordx4 v[236:239], v90, s[0:1] offset:192
	s_mul_i32 s99, s99, 0xe8000
	s_lshl_b32 s101, s100, 9
	s_add_i32 s99, s99, s101
	s_addk_i32 s99, 6144
	v_mul_u32_u24_e32 v92, 0x3a00, v86
	v_lshl_add_u32 v92, v87, 3, v92
	v_lshl_add_u32 v92, v88, 6, v92
	v_add_u32_e32 v92, s99, v92
	v_mov_b32_e32 v93, 0
	s_mov_b64 s[98:99], 0x3a000
	v_lshl_add_u64 v[120:121], v[92:93], 0, s[26:27]
	v_lshl_add_u64 v[122:123], v[120:121], 0, s[98:99]
	v_lshl_add_u64 v[124:125], v[122:123], 0, s[98:99]
	v_lshl_add_u64 v[126:127], v[124:125], 0, s[98:99]
	global_load_dwordx2 v[96:97], v[120:121], off offset:-2048
	global_load_dwordx2 v[98:99], v[120:121], off offset:-2016
	global_load_dwordx2 v[100:101], v[122:123], off offset:-2048
	global_load_dwordx2 v[102:103], v[122:123], off offset:-2016
	global_load_dwordx2 v[104:105], v[124:125], off offset:-2048
	global_load_dwordx2 v[106:107], v[124:125], off offset:-2016
	global_load_dwordx2 v[108:109], v[126:127], off offset:-2048
	global_load_dwordx2 v[110:111], v[126:127], off offset:-2016
	v_readlane_b32 s98, v255, 25
	v_readlane_b32 s99, v255, 26
	s_lshl_b32 s101, s100, 10
	s_addk_i32 s101, 0xe000
	v_lshl_add_u32 v94, v87, 4, s101
	v_lshl_add_u32 v94, v88, 7, v94
	s_nop 3
	global_load_dwordx4 v[112:115], v94, s[98:99]
	global_load_dwordx4 v[116:119], v94, s[98:99] offset:64
	v_cndmask_b32_e32 v20, 0, v49, vcc
	v_cmp_eq_u32_e32 vcc, 2, v1
	v_mul_f32_e32 v51, 0x3fb8aa3b, v72
	v_exp_f32_e32 v51, v51
	v_cndmask_b32_e32 v20, v20, v21, vcc
	v_cmp_eq_u32_e32 vcc, 3, v1
	v_mul_f32_e32 v29, v29, v51
	s_nop 0
	v_cndmask_b32_e32 v20, v20, v18, vcc
	v_cmp_eq_u32_e32 vcc, 4, v1
	v_mul_f32_e32 v51, 0x3fb8aa3b, v73
	v_exp_f32_e32 v51, v51
	v_cndmask_b32_e32 v19, v20, v19, vcc
	v_mul_f32_e32 v20, 0x3fb8aa3b, v71
	v_exp_f32_e32 v20, v20
	v_mul_f32_e32 v50, 0x3fb8aa3b, v19
	v_exp_f32_e32 v50, v50
	v_mul_f32_e32 v28, v28, v51
	v_mul_f32_e32 v20, v30, v20
	v_cvt_pk_bf16_f32 v30, v20, s0
	ds_write_b16 v191, v30 offset:2560
	v_mul_f32_e32 v30, 0xbfb8aa3b, v71
	v_exp_f32_e32 v30, v30
	v_mul_f32_e32 v20, v20, v50
	v_cvt_pk_bf16_f32 v20, v20, s0
	ds_write_b16 v191, v20 offset:19968
	v_mul_f32_e32 v20, v30, v54
	v_cvt_pk_bf16_f32 v30, v29, s0
	ds_write_b16 v191, v30 offset:2832
	v_mul_f32_e32 v30, 0xbfb8aa3b, v72
	v_exp_f32_e32 v30, v30
	v_mul_f32_e32 v29, v29, v50
	v_cvt_pk_bf16_f32 v29, v29, s0
	ds_write_b16 v191, v29 offset:20240
	v_mul_f32_e32 v29, v30, v52
	v_cvt_pk_bf16_f32 v30, v28, s0
	v_mul_f32_e32 v51, 0x3fb8aa3b, v74
	ds_write_b16 v191, v30 offset:3104
	v_mul_f32_e32 v30, 0xbfb8aa3b, v73
	v_exp_f32_e32 v51, v51
	v_exp_f32_e32 v30, v30
	v_mul_f32_e32 v28, v28, v50
	v_cvt_pk_bf16_f32 v28, v28, s0
	v_mul_f32_e32 v27, v27, v51
	ds_write_b16 v191, v28 offset:20512
	v_mul_f32_e32 v28, v30, v48
	v_cvt_pk_bf16_f32 v30, v27, s0
	v_mul_f32_e32 v48, 0x3fb8aa3b, v75
	ds_write_b16 v191, v30 offset:3376
	v_mul_f32_e32 v30, 0xbfb8aa3b, v74
	v_exp_f32_e32 v48, v48
	v_exp_f32_e32 v30, v30
	v_mul_f32_e32 v27, v27, v50
	v_cvt_pk_bf16_f32 v27, v27, s0
	v_mul_f32_e32 v25, v25, v48
	ds_write_b16 v191, v27 offset:20784
	v_mul_f32_e32 v27, v30, v47
	v_cvt_pk_bf16_f32 v30, v25, s0
	v_mul_f32_e32 v47, 0x3fb8aa3b, v76
	ds_write_b16 v191, v30 offset:3648
	v_mul_f32_e32 v30, 0xbfb8aa3b, v75
	v_exp_f32_e32 v47, v47
	v_exp_f32_e32 v30, v30
	v_mul_f32_e32 v25, v25, v50
	v_cvt_pk_bf16_f32 v25, v25, s0
	v_mul_f32_e32 v24, v24, v47
	ds_write_b16 v191, v25 offset:21056
	v_mul_f32_e32 v25, v30, v45
	v_cvt_pk_bf16_f32 v30, v24, s0
	v_mul_f32_e32 v45, 0x3fb8aa3b, v77
	ds_write_b16 v191, v30 offset:3920
	v_mul_f32_e32 v30, 0xbfb8aa3b, v76
	v_exp_f32_e32 v45, v45
	v_exp_f32_e32 v30, v30
	v_mul_f32_e32 v24, v24, v50
	v_cvt_pk_bf16_f32 v24, v24, s0
	v_mul_f32_e32 v23, v23, v45
	ds_write_b16 v191, v24 offset:21328
	v_mul_f32_e32 v24, v30, v43
	v_cvt_pk_bf16_f32 v30, v23, s0
	v_mul_f32_e32 v43, 0x3fb8aa3b, v78
	ds_write_b16 v191, v30 offset:4192
	v_mul_f32_e32 v30, 0xbfb8aa3b, v77
	v_exp_f32_e32 v43, v43
	v_exp_f32_e32 v30, v30
	v_mul_f32_e32 v23, v23, v50
	v_cvt_pk_bf16_f32 v23, v23, s0
	v_mul_f32_e32 v22, v22, v43
	ds_write_b16 v191, v23 offset:21600
	v_mul_f32_e32 v23, v30, v41
	v_cvt_pk_bf16_f32 v30, v22, s0
	v_mul_f32_e32 v41, 0x3fb8aa3b, v79
	ds_write_b16 v191, v30 offset:4464
	v_mul_f32_e32 v30, 0xbfb8aa3b, v78
	v_exp_f32_e32 v41, v41
	v_exp_f32_e32 v30, v30
	v_mul_f32_e32 v22, v22, v50
	v_cvt_pk_bf16_f32 v22, v22, s0
	v_mul_f32_e32 v26, v26, v41
	ds_write_b16 v191, v22 offset:21872
	v_mul_f32_e32 v22, v30, v39
	v_cvt_pk_bf16_f32 v30, v26, s0
	ds_write_b16 v191, v30 offset:4736
	v_mul_f32_e32 v30, 0xbfb8aa3b, v79
	v_exp_f32_e32 v30, v30
	v_mul_f32_e32 v39, 0x3fb8aa3b, v80
	v_exp_f32_e32 v39, v39
	v_mul_f32_e32 v26, v26, v50
	v_cvt_pk_bf16_f32 v26, v26, s0
	ds_write_b16 v191, v26 offset:22144
	v_mul_f32_e32 v26, v30, v46
	v_mul_f32_e32 v30, 0x3db504f3, v37
	v_mul_f32_e32 v30, v30, v39
	v_cvt_pk_bf16_f32 v37, v30, s0
	v_mul_f32_e32 v39, 0x3fb8aa3b, v81
	ds_write_b16 v191, v37 offset:5008
	v_mul_f32_e32 v37, 0xbfb8aa3b, v80
	v_exp_f32_e32 v39, v39
	v_exp_f32_e32 v37, v37
	v_mul_f32_e32 v30, v30, v50
	v_cvt_pk_bf16_f32 v30, v30, s0
	v_mul_f32_e32 v36, v36, v39
	ds_write_b16 v191, v30 offset:22416
	v_mul_f32_e32 v30, v37, v44
	v_cvt_pk_bf16_f32 v37, v36, s0
	v_mul_f32_e32 v39, 0x3fb8aa3b, v82
	ds_write_b16 v191, v37 offset:5280
	v_mul_f32_e32 v37, 0xbfb8aa3b, v81
	v_exp_f32_e32 v39, v39
	v_exp_f32_e32 v37, v37
	v_mul_f32_e32 v36, v36, v50
	v_cvt_pk_bf16_f32 v36, v36, s0
	v_mul_f32_e32 v35, v35, v39
	ds_write_b16 v191, v36 offset:22688
	v_mul_f32_e32 v36, v37, v42
	v_cvt_pk_bf16_f32 v37, v35, s0
	v_mul_f32_e32 v39, 0x3fb8aa3b, v83
	ds_write_b16 v191, v37 offset:5552
	v_mul_f32_e32 v37, 0xbfb8aa3b, v82
	v_exp_f32_e32 v39, v39
	v_exp_f32_e32 v37, v37
	v_mul_f32_e32 v35, v35, v50
	v_cvt_pk_bf16_f32 v35, v35, s0
	v_mul_f32_e32 v34, v34, v39
	ds_write_b16 v191, v35 offset:22960
	v_mul_f32_e32 v35, v37, v40
	v_cvt_pk_bf16_f32 v37, v34, s0
	v_mul_f32_e32 v39, 0x3fb8aa3b, v84
	ds_write_b16 v191, v37 offset:5824
	v_mul_f32_e32 v37, 0xbfb8aa3b, v83
	v_exp_f32_e32 v39, v39
	v_exp_f32_e32 v37, v37
	v_mul_f32_e32 v34, v34, v50
	v_cvt_pk_bf16_f32 v34, v34, s0
	v_mul_f32_e32 v33, v33, v39
	ds_write_b16 v191, v34 offset:23232
	v_mul_f32_e32 v34, v37, v38
	v_cvt_pk_bf16_f32 v37, v33, s0
	v_mul_f32_e32 v38, 0x3fb8aa3b, v55
	ds_write_b16 v191, v37 offset:6096
	v_mul_f32_e32 v37, 0xbfb8aa3b, v84
	v_exp_f32_e32 v38, v38
	v_exp_f32_e32 v37, v37
	v_mul_f32_e32 v33, v33, v50
	v_cvt_pk_bf16_f32 v33, v33, s0
	v_mul_f32_e32 v32, v32, v38
	ds_write_b16 v191, v33 offset:23504
	v_mul_f32_e32 v33, v37, v58
	v_cvt_pk_bf16_f32 v37, v32, s0
	v_mul_f32_e32 v38, 0x3fb8aa3b, v53
	ds_write_b16 v191, v37 offset:6368
	v_mul_f32_e32 v37, 0xbfb8aa3b, v55
	v_exp_f32_e32 v38, v38
	v_exp_f32_e32 v37, v37
	v_mul_f32_e32 v32, v32, v50
	v_cvt_pk_bf16_f32 v32, v32, s0
	v_mul_f32_e32 v31, v31, v38
	ds_write_b16 v191, v32 offset:23776
	v_mul_f32_e32 v32, v37, v59
	v_cvt_pk_bf16_f32 v37, v31, s0
	ds_write_b16 v191, v37 offset:6640
	v_mul_f32_e32 v37, 0xbfb8aa3b, v53
	v_exp_f32_e32 v37, v37
	v_mul_f32_e32 v31, v50, v31
	v_cvt_pk_bf16_f32 v31, v31, s0
	ds_write_b16 v191, v31 offset:24048
	v_mul_f32_e32 v31, v37, v60
	s_and_saveexec_b64 s[0:1], s[2:3]
	s_cbranch_execnz .LBB0_1394
	s_or_b64 exec, exec, s[0:1]
	s_and_saveexec_b64 s[0:1], s[4:5]
	s_cbranch_execnz .LBB0_1395

.LBB0_1345:
	s_or_b64 exec, exec, s[0:1]
	v_and_b32_e32 v18, 0xffff, v10
	v_lshrrev_b32_e32 v10, 16, v10
	v_lshl_or_b32 v18, v14, 16, v18
	v_add_u32_e32 v19, v182, v181
	v_and_or_b32 v10, v14, s66, v10
	ds_write2_b32 v19, v18, v10 offset1:36
	v_and_b32_e32 v10, 0xffff, v11
	v_lshrrev_b32_e32 v11, 16, v11
	v_lshl_or_b32 v10, v15, 16, v10
	v_and_or_b32 v11, v15, s66, v11
	ds_write2_b32 v19, v10, v11 offset0:72 offset1:108
	v_and_b32_e32 v10, 0xffff, v12
	v_lshrrev_b32_e32 v11, 16, v12
	v_lshl_or_b32 v10, v16, 16, v10
	v_and_or_b32 v11, v16, s66, v11
	ds_write2_b32 v19, v10, v11 offset0:144 offset1:180
	v_and_b32_e32 v10, 0xffff, v13
	v_lshrrev_b32_e32 v11, 16, v13
	v_lshl_or_b32 v10, v17, 16, v10
	v_and_or_b32 v11, v17, s66, v11
	ds_write2_b32 v19, v10, v11 offset0:216 offset1:252
	v_and_b32_e32 v10, 0xffff, v2
	v_lshrrev_b32_e32 v2, 16, v2
	v_lshl_or_b32 v10, v6, 16, v10
	v_and_or_b32 v2, v6, s66, v2
	s_ashr_i32 s21, s20, 31
	s_mul_i32 s0, s20, 0xfffa0000
	ds_write2_b32 v192, v10, v2 offset1:36
	v_and_b32_e32 v2, 0xffff, v3
	v_lshrrev_b32_e32 v3, 16, v3
	s_lshr_b32 s72, s69, 6
	s_add_i32 s0, s51, s0
	s_lshl_b64 s[40:41], s[20:21], 18
	v_lshl_or_b32 v2, v7, 16, v2
	v_and_or_b32 v3, v7, s66, v3
	s_add_u32 s21, s44, s40
	s_mov_b32 s1, s25
	ds_write2_b32 v192, v2, v3 offset0:72 offset1:108
	v_and_b32_e32 v2, 0xffff, v4
	v_lshrrev_b32_e32 v3, 16, v4
	s_addc_u32 s40, s45, s41
	s_lshl_b64 s[0:1], s[0:1], 1
	v_lshl_or_b32 v2, v8, 16, v2
	v_and_or_b32 v3, v8, s66, v3
	s_add_u32 s0, s21, s0
	ds_write2_b32 v192, v2, v3 offset0:144 offset1:180
	v_and_b32_e32 v2, 0xffff, v5
	v_lshrrev_b32_e32 v3, 16, v5
	s_addc_u32 s1, s40, s1
	v_lshl_or_b32 v2, v9, 16, v2
	v_and_or_b32 v3, v9, s66, v3
	v_or_b32_e32 v176, s70, v139
	v_lshlrev_b32_e32 v136, 1, v140
	ds_write2_b32 v192, v2, v3 offset0:216 offset1:252
	v_lshl_add_u64 v[2:3], s[0:1], 0, v[136:137]
	v_or_b32_e32 v136, 16, v176
	v_lshlrev_b64 v[6:7], 8, v[136:137]
	v_or_b32_e32 v136, 32, v176
	v_lshl_add_u64 v[14:15], v[2:3], 0, v[6:7]
	v_lshlrev_b64 v[6:7], 8, v[136:137]
	v_or_b32_e32 v136, 48, v176
	v_lshl_add_u64 v[18:19], v[2:3], 0, v[6:7]
	v_lshlrev_b64 v[6:7], 8, v[136:137]
	v_or_b32_e32 v136, 64, v176
	v_lshl_add_u64 v[26:27], v[2:3], 0, v[6:7]
	v_lshlrev_b64 v[6:7], 8, v[136:137]
	v_or_b32_e32 v136, 0x50, v176
	v_lshl_add_u64 v[34:35], v[2:3], 0, v[6:7]
	v_lshlrev_b64 v[6:7], 8, v[136:137]
	v_or_b32_e32 v136, 0x60, v176
	v_mov_b32_e32 v177, v137
	v_lshl_add_u64 v[42:43], v[2:3], 0, v[6:7]
	v_lshlrev_b64 v[6:7], 8, v[136:137]
	v_or_b32_e32 v136, 0x70, v176
	v_lshlrev_b64 v[4:5], 8, v[176:177]
	v_lshl_add_u64 v[50:51], v[2:3], 0, v[6:7]
	v_lshlrev_b64 v[6:7], 8, v[136:137]
	v_lshl_add_u64 v[4:5], v[2:3], 0, v[4:5]
	v_lshl_add_u64 v[2:3], v[2:3], 0, v[6:7]
	s_waitcnt lgkmcnt(0)
	s_barrier
	s_cmpk_gt_u32 s69, 0x2ff
	s_cbranch_scc1 .LBB0_1354
	s_cmpk_lt_u32 s69, 0x280
	s_mov_b64 s[0:1], -1
	s_cbranch_scc1 .LBB0_1400
	s_andn2_b64 vcc, exec, s[0:1]
	s_cbranch_vccz .LBB0_1401

.LBB0_1362:
	v_mad_u32_u24 v136, v149, s43, v142
	s_waitcnt lgkmcnt(0)
	s_barrier
	v_and_b32_e32 v128, 15, v0
	v_bfe_u32 v129, v0, 4, 2
	v_lshrrev_b32_e32 v130, 6, v0
	v_mul_u32_u24_e32 v131, 0x110, v128
	v_lshl_add_u32 v131, v129, 4, v131
	v_mul_u32_u24_e32 v132, 0x90, v128
	v_lshl_add_u32 v132, v129, 4, v132
	v_mul_u32_u24_e32 v133, 4608, v130
	v_add_u32_e32 v133, v133, v132
	v_add_u32_e32 v133, 0x16000, v133
	v_add_u32_e32 v132, 0x13c00, v132
	v_lshlrev_b32_e32 v83, 5, v128
	v_lshl_add_u32 v82, v130, 2, v83
	v_mov_b32_e32 v84, 0x358637bd
	s_waitcnt vmcnt(0)
	ds_read_b128 v[34:37], v133
	ds_read_b128 v[38:41], v133 offset:2304
	ds_read_b128 v[42:45], v133 offset:64
	ds_read_b128 v[46:49], v133 offset:2368
	ds_read_b128 v[50:53], v131 offset:19968
	ds_read_b128 v[54:57], v131 offset:20032
	ds_read_b128 v[58:61], v131 offset:20096
	ds_read_b128 v[62:65], v131 offset:20160
	ds_read_b128 v[160:163], v132
	ds_read_b128 v[66:69], v131 offset:24320
	ds_read_b128 v[70:73], v131 offset:24384
	ds_read_b128 v[74:77], v131 offset:24448
	ds_read_b128 v[78:81], v131 offset:24512
	ds_read_b128 v[168:171], v132 offset:2304
	s_waitcnt lgkmcnt(5)
	v_mfma_f32_16x16x32_bf16 v[2:5], v[208:211], v[50:53], 0
	v_mfma_f32_16x16x32_bf16 v[6:9], v[224:227], v[50:53], 0
	v_mfma_f32_16x16x32_bf16 v[2:5], v[212:215], v[54:57], v[2:5]
	v_mfma_f32_16x16x32_bf16 v[6:9], v[228:231], v[54:57], v[6:9]
	v_mfma_f32_16x16x32_bf16 v[2:5], v[216:219], v[58:61], v[2:5]
	v_mfma_f32_16x16x32_bf16 v[6:9], v[232:235], v[58:61], v[6:9]
	v_mfma_f32_16x16x32_bf16 v[2:5], v[220:223], v[62:65], v[2:5]
	v_mfma_f32_16x16x32_bf16 v[6:9], v[236:239], v[62:65], v[6:9]
	v_mfma_f32_16x16x32_bf16 v[2:5], v[34:37], v[160:163], v[2:5]
	v_mfma_f32_16x16x32_bf16 v[6:9], v[38:41], v[160:163], v[6:9]
	ds_read_b128 v[50:53], v131 offset:28672
	ds_read_b128 v[54:57], v131 offset:28736
	ds_read_b128 v[58:61], v131 offset:28800
	ds_read_b128 v[62:65], v131 offset:28864
	ds_read_b128 v[160:163], v132 offset:4608
	ds_read_b128 v[164:167], v132 offset:4672
	s_waitcnt lgkmcnt(6)
	v_mfma_f32_16x16x32_bf16 v[10:13], v[208:211], v[66:69], 0
	v_mfma_f32_16x16x32_bf16 v[14:17], v[224:227], v[66:69], 0
	v_mfma_f32_16x16x32_bf16 v[10:13], v[212:215], v[70:73], v[10:13]
	v_mfma_f32_16x16x32_bf16 v[14:17], v[228:231], v[70:73], v[14:17]
	v_mfma_f32_16x16x32_bf16 v[10:13], v[216:219], v[74:77], v[10:13]
	v_mfma_f32_16x16x32_bf16 v[14:17], v[232:235], v[74:77], v[14:17]
	v_mfma_f32_16x16x32_bf16 v[10:13], v[220:223], v[78:81], v[10:13]
	v_mfma_f32_16x16x32_bf16 v[14:17], v[236:239], v[78:81], v[14:17]
	v_mfma_f32_16x16x32_bf16 v[10:13], v[34:37], v[168:171], v[10:13]
	v_mfma_f32_16x16x32_bf16 v[14:17], v[38:41], v[168:171], v[14:17]
	ds_read_b128 v[66:69], v131 offset:33024
	ds_read_b128 v[70:73], v131 offset:33088
	ds_read_b128 v[74:77], v131 offset:33152
	ds_read_b128 v[78:81], v131 offset:33216
	ds_read_b128 v[168:171], v132 offset:6912
	ds_read_b128 v[172:175], v132 offset:6976
	s_waitcnt lgkmcnt(6)
	v_mfma_f32_16x16x32_bf16 v[18:21], v[208:211], v[50:53], 0
	v_mfma_f32_16x16x32_bf16 v[22:25], v[224:227], v[50:53], 0
	v_mfma_f32_16x16x32_bf16 v[18:21], v[212:215], v[54:57], v[18:21]
	v_mfma_f32_16x16x32_bf16 v[22:25], v[228:231], v[54:57], v[22:25]
	v_mfma_f32_16x16x32_bf16 v[18:21], v[216:219], v[58:61], v[18:21]
	v_mfma_f32_16x16x32_bf16 v[22:25], v[232:235], v[58:61], v[22:25]
	v_mfma_f32_16x16x32_bf16 v[18:21], v[220:223], v[62:65], v[18:21]
	v_mfma_f32_16x16x32_bf16 v[22:25], v[236:239], v[62:65], v[22:25]
	v_mfma_f32_16x16x32_bf16 v[18:21], v[34:37], v[160:163], v[18:21]
	v_mfma_f32_16x16x32_bf16 v[22:25], v[38:41], v[160:163], v[22:25]
	v_mfma_f32_16x16x32_bf16 v[18:21], v[42:45], v[164:167], v[18:21]
	v_mfma_f32_16x16x32_bf16 v[22:25], v[46:49], v[164:167], v[22:25]
	s_waitcnt lgkmcnt(0)
	v_mfma_f32_16x16x32_bf16 v[26:29], v[208:211], v[66:69], 0
	v_mfma_f32_16x16x32_bf16 v[30:33], v[224:227], v[66:69], 0
	v_mfma_f32_16x16x32_bf16 v[26:29], v[212:215], v[70:73], v[26:29]
	v_mfma_f32_16x16x32_bf16 v[30:33], v[228:231], v[70:73], v[30:33]
	v_mfma_f32_16x16x32_bf16 v[26:29], v[216:219], v[74:77], v[26:29]
	v_mfma_f32_16x16x32_bf16 v[30:33], v[232:235], v[74:77], v[30:33]
	v_mfma_f32_16x16x32_bf16 v[26:29], v[220:223], v[78:81], v[26:29]
	v_mfma_f32_16x16x32_bf16 v[30:33], v[236:239], v[78:81], v[30:33]
	v_mfma_f32_16x16x32_bf16 v[26:29], v[34:37], v[168:171], v[26:29]
	v_mfma_f32_16x16x32_bf16 v[30:33], v[38:41], v[168:171], v[30:33]
	v_mfma_f32_16x16x32_bf16 v[26:29], v[42:45], v[172:175], v[26:29]
	v_mfma_f32_16x16x32_bf16 v[30:33], v[46:49], v[172:175], v[30:33]
	s_nop 7
	s_nop 1
	v_mul_f32_e32 v176, v2, v2
	v_fmac_f32_e32 v176, v3, v3
	v_fmac_f32_e32 v176, v4, v4
	v_fmac_f32_e32 v176, v5, v5
	v_fmac_f32_e32 v176, v6, v6
	v_fmac_f32_e32 v176, v7, v7
	v_fmac_f32_e32 v176, v8, v8
	v_fmac_f32_e32 v176, v9, v9
	v_mul_f32_e32 v177, v10, v10
	v_fmac_f32_e32 v177, v11, v11
	v_fmac_f32_e32 v177, v12, v12
	v_fmac_f32_e32 v177, v13, v13
	v_fmac_f32_e32 v177, v14, v14
	v_fmac_f32_e32 v177, v15, v15
	v_fmac_f32_e32 v177, v16, v16
	v_fmac_f32_e32 v177, v17, v17
	v_mul_f32_e32 v86, v18, v18
	v_fmac_f32_e32 v86, v19, v19
	v_fmac_f32_e32 v86, v20, v20
	v_fmac_f32_e32 v86, v21, v21
	v_fmac_f32_e32 v86, v22, v22
	v_fmac_f32_e32 v86, v23, v23
	v_fmac_f32_e32 v86, v24, v24
	v_fmac_f32_e32 v86, v25, v25
	v_mul_f32_e32 v87, v26, v26
	v_fmac_f32_e32 v87, v27, v27
	v_fmac_f32_e32 v87, v28, v28
	v_fmac_f32_e32 v87, v29, v29
	v_fmac_f32_e32 v87, v30, v30
	v_fmac_f32_e32 v87, v31, v31
	v_fmac_f32_e32 v87, v32, v32
	v_fmac_f32_e32 v87, v33, v33
	ds_swizzle_b32 v88, v176 offset:0x401F
	ds_swizzle_b32 v89, v177 offset:0x401F
	ds_swizzle_b32 v90, v86 offset:0x401F
	ds_swizzle_b32 v91, v87 offset:0x401F
	s_waitcnt lgkmcnt(0)
	v_add_f32_e32 v176, v176, v88
	v_add_f32_e32 v177, v177, v89
	v_add_f32_e32 v86, v86, v90
	v_add_f32_e32 v87, v87, v91
	v_mov_b32_e32 v88, v176
	v_mov_b32_e32 v89, v177
	v_mov_b32_e32 v90, v86
	v_mov_b32_e32 v91, v87
	s_nop 1
	v_permlane32_swap_b32_e32 v88, v176
	v_permlane32_swap_b32_e32 v89, v177
	v_permlane32_swap_b32_e32 v90, v86
	v_permlane32_swap_b32_e32 v91, v87
	s_nop 1
	v_add_f32_e32 v176, v176, v88
	v_add_f32_e32 v177, v177, v89
	v_add_f32_e32 v86, v86, v90
	v_add_f32_e32 v87, v87, v91
	ds_write_b32 v82, v176
	ds_write_b32 v82, v177 offset:512
	ds_write_b32 v82, v86 offset:1024
	ds_write_b32 v82, v87 offset:1536
	s_waitcnt lgkmcnt(0)
	s_barrier
	ds_read_b128 v[50:53], v83
	ds_read_b128 v[54:57], v83 offset:16
	ds_read_b128 v[58:61], v83 offset:512
	ds_read_b128 v[62:65], v83 offset:528
	ds_read_b128 v[66:69], v83 offset:1024
	ds_read_b128 v[70:73], v83 offset:1040
	ds_read_b128 v[74:77], v83 offset:1536
	ds_read_b128 v[78:81], v83 offset:1552
	s_waitcnt lgkmcnt(0)
	s_barrier
	v_add_f32_e32 v50, v50, v51
	v_add_f32_e32 v52, v52, v53
	v_add_f32_e32 v54, v54, v55
	v_add_f32_e32 v56, v56, v57
	v_add_f32_e32 v50, v50, v52
	v_add_f32_e32 v54, v54, v56
	v_add_f32_e32 v50, v50, v54
	v_fmamk_f32 v50, v50, 0x3b800000, v84
	v_rsq_f32_e32 v176, v50
	v_add_f32_e32 v58, v58, v59
	v_add_f32_e32 v60, v60, v61
	v_add_f32_e32 v62, v62, v63
	v_add_f32_e32 v64, v64, v65
	v_add_f32_e32 v58, v58, v60
	v_add_f32_e32 v62, v62, v64
	v_add_f32_e32 v58, v58, v62
	v_fmamk_f32 v58, v58, 0x3b800000, v84
	v_rsq_f32_e32 v177, v58
	v_add_f32_e32 v66, v66, v67
	v_add_f32_e32 v68, v68, v69
	v_add_f32_e32 v70, v70, v71
	v_add_f32_e32 v72, v72, v73
	v_add_f32_e32 v66, v66, v68
	v_add_f32_e32 v70, v70, v72
	v_add_f32_e32 v66, v66, v70
	v_fmamk_f32 v66, v66, 0x3b800000, v84
	v_rsq_f32_e32 v86, v66
	v_add_f32_e32 v74, v74, v75
	v_add_f32_e32 v76, v76, v77
	v_add_f32_e32 v78, v78, v79
	v_add_f32_e32 v80, v80, v81
	v_add_f32_e32 v74, v74, v76
	v_add_f32_e32 v78, v78, v80
	v_add_f32_e32 v74, v74, v78
	v_fmamk_f32 v74, v74, 0x3b800000, v84
	v_rsq_f32_e32 v87, v74
	v_lshlrev_b32_e32 v66, 16, v96
	v_and_b32_e32 v67, 0xffff0000, v96
	v_lshlrev_b32_e32 v68, 16, v97
	v_and_b32_e32 v69, 0xffff0000, v97
	v_mul_f32_e32 v2, v2, v176
	v_mul_f32_e32 v3, v3, v176
	v_mul_f32_e32 v4, v4, v176
	v_mul_f32_e32 v5, v5, v176
	v_mul_f32_e32 v2, v2, v112
	v_mul_f32_e32 v3, v3, v113
	v_mul_f32_e32 v4, v4, v114
	v_mul_f32_e32 v5, v5, v115
	v_mul_f32_e32 v2, v2, v66
	v_mul_f32_e32 v3, v3, v67
	v_mul_f32_e32 v4, v4, v68
	v_mul_f32_e32 v5, v5, v69
	v_cvt_pk_bf16_f32 v2, v2, v3
	v_cvt_pk_bf16_f32 v3, v4, v5
	global_store_dwordx2 v[120:121], v[2:3], off offset:2048
	v_lshlrev_b32_e32 v66, 16, v98
	v_and_b32_e32 v67, 0xffff0000, v98
	v_lshlrev_b32_e32 v68, 16, v99
	v_and_b32_e32 v69, 0xffff0000, v99
	v_mul_f32_e32 v6, v6, v176
	v_mul_f32_e32 v7, v7, v176
	v_mul_f32_e32 v8, v8, v176
	v_mul_f32_e32 v9, v9, v176
	v_mul_f32_e32 v6, v6, v116
	v_mul_f32_e32 v7, v7, v117
	v_mul_f32_e32 v8, v8, v118
	v_mul_f32_e32 v9, v9, v119
	v_mul_f32_e32 v6, v6, v66
	v_mul_f32_e32 v7, v7, v67
	v_mul_f32_e32 v8, v8, v68
	v_mul_f32_e32 v9, v9, v69
	v_cvt_pk_bf16_f32 v6, v6, v7
	v_cvt_pk_bf16_f32 v7, v8, v9
	global_store_dwordx2 v[120:121], v[6:7], off offset:2080
	v_lshlrev_b32_e32 v66, 16, v100
	v_and_b32_e32 v67, 0xffff0000, v100
	v_lshlrev_b32_e32 v68, 16, v101
	v_and_b32_e32 v69, 0xffff0000, v101
	v_mul_f32_e32 v10, v10, v177
	v_mul_f32_e32 v11, v11, v177
	v_mul_f32_e32 v12, v12, v177
	v_mul_f32_e32 v13, v13, v177
	v_mul_f32_e32 v10, v10, v112
	v_mul_f32_e32 v11, v11, v113
	v_mul_f32_e32 v12, v12, v114
	v_mul_f32_e32 v13, v13, v115
	v_mul_f32_e32 v10, v10, v66
	v_mul_f32_e32 v11, v11, v67
	v_mul_f32_e32 v12, v12, v68
	v_mul_f32_e32 v13, v13, v69
	v_cvt_pk_bf16_f32 v10, v10, v11
	v_cvt_pk_bf16_f32 v11, v12, v13
	global_store_dwordx2 v[122:123], v[10:11], off offset:2048
	v_lshlrev_b32_e32 v66, 16, v102
	v_and_b32_e32 v67, 0xffff0000, v102
	v_lshlrev_b32_e32 v68, 16, v103
	v_and_b32_e32 v69, 0xffff0000, v103
	v_mul_f32_e32 v14, v14, v177
	v_mul_f32_e32 v15, v15, v177
	v_mul_f32_e32 v16, v16, v177
	v_mul_f32_e32 v17, v17, v177
	v_mul_f32_e32 v14, v14, v116
	v_mul_f32_e32 v15, v15, v117
	v_mul_f32_e32 v16, v16, v118
	v_mul_f32_e32 v17, v17, v119
	v_mul_f32_e32 v14, v14, v66
	v_mul_f32_e32 v15, v15, v67
	v_mul_f32_e32 v16, v16, v68
	v_mul_f32_e32 v17, v17, v69
	v_cvt_pk_bf16_f32 v14, v14, v15
	v_cvt_pk_bf16_f32 v15, v16, v17
	global_store_dwordx2 v[122:123], v[14:15], off offset:2080
	v_lshlrev_b32_e32 v66, 16, v104
	v_and_b32_e32 v67, 0xffff0000, v104
	v_lshlrev_b32_e32 v68, 16, v105
	v_and_b32_e32 v69, 0xffff0000, v105
	v_mul_f32_e32 v18, v18, v86
	v_mul_f32_e32 v19, v19, v86
	v_mul_f32_e32 v20, v20, v86
	v_mul_f32_e32 v21, v21, v86
	v_mul_f32_e32 v18, v18, v112
	v_mul_f32_e32 v19, v19, v113
	v_mul_f32_e32 v20, v20, v114
	v_mul_f32_e32 v21, v21, v115
	v_mul_f32_e32 v18, v18, v66
	v_mul_f32_e32 v19, v19, v67
	v_mul_f32_e32 v20, v20, v68
	v_mul_f32_e32 v21, v21, v69
	v_cvt_pk_bf16_f32 v18, v18, v19
	v_cvt_pk_bf16_f32 v19, v20, v21
	global_store_dwordx2 v[124:125], v[18:19], off offset:2048
	v_lshlrev_b32_e32 v66, 16, v106
	v_and_b32_e32 v67, 0xffff0000, v106
	v_lshlrev_b32_e32 v68, 16, v107
	v_and_b32_e32 v69, 0xffff0000, v107
	v_mul_f32_e32 v22, v22, v86
	v_mul_f32_e32 v23, v23, v86
	v_mul_f32_e32 v24, v24, v86
	v_mul_f32_e32 v25, v25, v86
	v_mul_f32_e32 v22, v22, v116
	v_mul_f32_e32 v23, v23, v117
	v_mul_f32_e32 v24, v24, v118
	v_mul_f32_e32 v25, v25, v119
	v_mul_f32_e32 v22, v22, v66
	v_mul_f32_e32 v23, v23, v67
	v_mul_f32_e32 v24, v24, v68
	v_mul_f32_e32 v25, v25, v69
	v_cvt_pk_bf16_f32 v22, v22, v23
	v_cvt_pk_bf16_f32 v23, v24, v25
	global_store_dwordx2 v[124:125], v[22:23], off offset:2080
	v_lshlrev_b32_e32 v66, 16, v108
	v_and_b32_e32 v67, 0xffff0000, v108
	v_lshlrev_b32_e32 v68, 16, v109
	v_and_b32_e32 v69, 0xffff0000, v109
	v_mul_f32_e32 v26, v26, v87
	v_mul_f32_e32 v27, v27, v87
	v_mul_f32_e32 v28, v28, v87
	v_mul_f32_e32 v29, v29, v87
	v_mul_f32_e32 v26, v26, v112
	v_mul_f32_e32 v27, v27, v113
	v_mul_f32_e32 v28, v28, v114
	v_mul_f32_e32 v29, v29, v115
	v_mul_f32_e32 v26, v26, v66
	v_mul_f32_e32 v27, v27, v67
	v_mul_f32_e32 v28, v28, v68
	v_mul_f32_e32 v29, v29, v69
	v_cvt_pk_bf16_f32 v26, v26, v27
	v_cvt_pk_bf16_f32 v27, v28, v29
	global_store_dwordx2 v[126:127], v[26:27], off offset:2048
	v_lshlrev_b32_e32 v66, 16, v110
	v_and_b32_e32 v67, 0xffff0000, v110
	v_lshlrev_b32_e32 v68, 16, v111
	v_and_b32_e32 v69, 0xffff0000, v111
	v_mul_f32_e32 v30, v30, v87
	v_mul_f32_e32 v31, v31, v87
	v_mul_f32_e32 v32, v32, v87
	v_mul_f32_e32 v33, v33, v87
	v_mul_f32_e32 v30, v30, v116
	v_mul_f32_e32 v31, v31, v117
	v_mul_f32_e32 v32, v32, v118
	v_mul_f32_e32 v33, v33, v119
	v_mul_f32_e32 v30, v30, v66
	v_mul_f32_e32 v31, v31, v67
	v_mul_f32_e32 v32, v32, v68
	v_mul_f32_e32 v33, v33, v69
	v_cvt_pk_bf16_f32 v30, v30, v31
	v_cvt_pk_bf16_f32 v31, v32, v33
	global_store_dwordx2 v[126:127], v[30:31], off offset:2080
	s_branch .LBB0_1338
.LBB0_1367:
	s_and_b64 vcc, exec, s[0:1]
	s_cbranch_vccz .LBB0_1338
	s_add_i32 s24, s46, s37
	s_add_i32 s38, s24, 0xffffec00
	s_ashr_i32 s39, s38, 31
	s_lshl_b32 s69, s20, 6
	v_or_b32_e32 v20, s69, v135
	s_lshl_b64 s[40:41], s[38:39], 1
	v_lshl_add_u64 v[2:3], v[146:147], 0, s[40:41]
	v_or_b32_e32 v6, 1, v20
	v_mad_i64_i32 v[4:5], s[0:1], v20, s53, v[2:3]
	v_mad_i64_i32 v[6:7], s[0:1], v6, s53, v[2:3]
	v_or_b32_e32 v8, 2, v20
	v_or_b32_e32 v10, 3, v20
	v_or_b32_e32 v12, 4, v20
	v_or_b32_e32 v14, 5, v20
	v_or_b32_e32 v16, 6, v20
	v_or_b32_e32 v18, 7, v20
	v_mad_i64_i32 v[8:9], s[0:1], v8, s53, v[2:3]
	v_mad_i64_i32 v[10:11], s[0:1], v10, s53, v[2:3]
	v_mad_i64_i32 v[12:13], s[0:1], v12, s53, v[2:3]
	v_mad_i64_i32 v[14:15], s[0:1], v14, s53, v[2:3]
	v_mad_i64_i32 v[16:17], s[0:1], v16, s53, v[2:3]
	v_mad_i64_i32 v[18:19], s[0:1], v18, s53, v[2:3]
	global_load_ushort v21, v[4:5], off
	global_load_ushort v22, v[6:7], off
	global_load_ushort v23, v[8:9], off
	global_load_ushort v24, v[10:11], off
	global_load_ushort v25, v[12:13], off
	global_load_ushort v26, v[14:15], off
	global_load_ushort v27, v[16:17], off
	global_load_ushort v28, v[18:19], off
	v_or_b32_e32 v4, 8, v20
	v_or_b32_e32 v6, 9, v20
	v_mad_i64_i32 v[4:5], s[0:1], v4, s53, v[2:3]
	v_mad_i64_i32 v[6:7], s[0:1], v6, s53, v[2:3]
	v_or_b32_e32 v8, 10, v20
	v_or_b32_e32 v10, 11, v20
	v_or_b32_e32 v12, 12, v20
	v_or_b32_e32 v14, 13, v20
	v_or_b32_e32 v16, 14, v20
	v_or_b32_e32 v18, 15, v20
	v_mad_i64_i32 v[8:9], s[0:1], v8, s53, v[2:3]
	v_mad_i64_i32 v[10:11], s[0:1], v10, s53, v[2:3]
	v_mad_i64_i32 v[12:13], s[0:1], v12, s53, v[2:3]
	v_mad_i64_i32 v[14:15], s[0:1], v14, s53, v[2:3]
	v_mad_i64_i32 v[16:17], s[0:1], v16, s53, v[2:3]
	v_mad_i64_i32 v[2:3], s[0:1], v18, s53, v[2:3]
	global_load_ushort v20, v[4:5], off
	global_load_ushort v29, v[6:7], off
	global_load_ushort v30, v[8:9], off
	global_load_ushort v31, v[10:11], off
	global_load_ushort v32, v[12:13], off
	global_load_ushort v33, v[14:15], off
	global_load_ushort v34, v[16:17], off
	global_load_ushort v35, v[2:3], off
	v_add_u32_e32 v6, s24, v134
	v_add_u32_e32 v2, 0xffffec00, v6
	v_readlane_b32 s72, v255, 13
	v_ashrrev_i32_e32 v3, 31, v2
	v_readlane_b32 s76, v255, 17
	v_readlane_b32 s77, v255, 18
	v_or_b32_e32 v38, s69, v188
	v_mov_b64_e32 v[74:75], s[26:27]
	v_lshl_add_u64 v[2:3], v[2:3], 2, s[76:77]
	v_add_co_u32_e32 v4, vcc, s48, v2
	v_or_b32_e32 v10, 3, v38
	s_nop 0
	v_addc_co_u32_e32 v5, vcc, 0, v3, vcc
	global_load_dword v36, v[2:3], off
	global_load_dword v37, v[4:5], off
	v_add_u32_e32 v2, 0xfffff000, v6
	v_ashrrev_i32_e32 v3, 31, v2
	v_or_b32_e32 v12, 4, v38
	v_or_b32_e32 v14, 5, v38
	v_mad_i64_i32 v[4:5], s[0:1], v38, s53, v[74:75]
	v_lshlrev_b64 v[2:3], 1, v[2:3]
	v_or_b32_e32 v6, 1, v38
	v_or_b32_e32 v8, 2, v38
	v_mad_i64_i32 v[10:11], s[0:1], v10, s53, v[74:75]
	v_mad_i64_i32 v[12:13], s[0:1], v12, s53, v[74:75]
	v_mad_i64_i32 v[14:15], s[0:1], v14, s53, v[74:75]
	v_or_b32_e32 v16, 6, v38
	v_or_b32_e32 v18, 7, v38
	v_lshl_add_u64 v[4:5], v[4:5], 0, v[2:3]
	v_mad_i64_i32 v[6:7], s[0:1], v6, s53, v[74:75]
	v_mad_i64_i32 v[8:9], s[0:1], v8, s53, v[74:75]
	v_lshl_add_u64 v[10:11], v[10:11], 0, v[2:3]
	v_lshl_add_u64 v[12:13], v[12:13], 0, v[2:3]
	v_lshl_add_u64 v[14:15], v[14:15], 0, v[2:3]
	v_mad_i64_i32 v[16:17], s[0:1], v16, s53, v[74:75]
	v_mad_i64_i32 v[18:19], s[0:1], v18, s53, v[74:75]
	v_lshl_add_u64 v[6:7], v[6:7], 0, v[2:3]
	v_lshl_add_u64 v[8:9], v[8:9], 0, v[2:3]
	v_lshl_add_u64 v[16:17], v[16:17], 0, v[2:3]
	v_lshl_add_u64 v[18:19], v[18:19], 0, v[2:3]
	global_load_ushort v39, v[4:5], off
	global_load_ushort v40, v[6:7], off
	global_load_ushort v41, v[8:9], off
	global_load_ushort v42, v[10:11], off
	s_nop 0
	global_load_ushort v12, v[12:13], off
	s_nop 0
	global_load_ushort v13, v[14:15], off
	s_nop 0
	global_load_ushort v14, v[16:17], off
	global_load_ushort v15, v[18:19], off
	v_or_b32_e32 v4, 8, v38
	v_or_b32_e32 v10, 11, v38
	v_mad_i64_i32 v[4:5], s[0:1], v4, s53, v[74:75]
	v_or_b32_e32 v6, 9, v38
	v_or_b32_e32 v8, 10, v38
	v_mad_i64_i32 v[10:11], s[0:1], v10, s53, v[74:75]
	v_lshl_add_u64 v[4:5], v[4:5], 0, v[2:3]
	v_mad_i64_i32 v[6:7], s[0:1], v6, s53, v[74:75]
	v_mad_i64_i32 v[8:9], s[0:1], v8, s53, v[74:75]
	v_lshl_add_u64 v[10:11], v[10:11], 0, v[2:3]
	v_lshl_add_u64 v[6:7], v[6:7], 0, v[2:3]
	v_lshl_add_u64 v[8:9], v[8:9], 0, v[2:3]
	global_load_ushort v16, v[4:5], off
	global_load_ushort v17, v[6:7], off
	global_load_ushort v18, v[8:9], off
	s_nop 0
	global_load_ushort v10, v[10:11], off
	v_or_b32_e32 v4, 12, v38
	v_or_b32_e32 v6, 13, v38
	v_mad_i64_i32 v[4:5], s[0:1], v4, s53, v[74:75]
	v_mad_i64_i32 v[6:7], s[0:1], v6, s53, v[74:75]
	v_lshl_add_u64 v[4:5], v[4:5], 0, v[2:3]
	v_lshl_add_u64 v[6:7], v[6:7], 0, v[2:3]
	global_load_ushort v19, v[4:5], off
	global_load_ushort v43, v[6:7], off
	v_or_b32_e32 v4, 14, v38
	v_or_b32_e32 v6, 15, v38
	v_mad_i64_i32 v[4:5], s[0:1], v4, s53, v[74:75]
	v_mad_i64_i32 v[6:7], s[0:1], v6, s53, v[74:75]
	s_ashr_i32 s21, s20, 31
	s_ashr_i32 s37, s36, 31
	s_lshl_b64 s[0:1], s[20:21], 18
	s_lshl_b64 s[20:21], s[36:37], 15
	s_add_u32 s0, s90, s0
	v_lshl_add_u64 v[4:5], v[4:5], 0, v[2:3]
	s_waitcnt vmcnt(0)
	v_lshlrev_b32_e32 v93, 16, v20
	s_addc_u32 s1, s91, s1
	v_lshl_add_u64 v[2:3], v[6:7], 0, v[2:3]
	global_load_ushort v38, v[4:5], off
	global_load_ushort v44, v[2:3], off
	v_lshlrev_b32_e32 v98, 16, v24
	s_add_u32 s36, s0, s20
	s_addc_u32 s37, s1, s21
	v_sub_f32_e32 v4, v36, v37
	v_mul_f32_e32 v4, 0x3fb8aa3b, v4
	s_mul_hi_i32 s0, s69, 0x3a00
	s_add_u32 s20, s26, s68
	v_exp_f32_e32 v11, v4
	s_addc_u32 s21, s27, s0
	s_lshl_b64 s[0:1], s[24:25], 1
	s_add_u32 s0, s20, s0
	v_lshlrev_b32_e32 v97, 16, v25
	s_addc_u32 s1, s21, s1
	v_mov_b32_e32 v153, v137
	v_lshlrev_b32_e32 v96, 16, v26
	v_lshl_add_u64 v[2:3], s[0:1], 0, v[152:153]
	v_mov_b32_e32 v155, v137
	v_add_f32_e32 v11, 1.0, v11
	v_lshl_add_u64 v[2:3], v[2:3], 0, v[154:155]
	v_rcp_f32_e32 v11, v11
	v_add_co_u32_e32 v6, vcc, s55, v2
	v_lshlrev_b32_e32 v94, 16, v28
	s_nop 0
	v_addc_co_u32_e32 v7, vcc, 0, v3, vcc
	v_lshlrev_b32_e32 v101, 16, v21
	v_lshlrev_b32_e32 v91, 16, v30
	v_lshlrev_b32_e32 v90, 16, v31
	v_lshlrev_b32_e32 v100, 16, v22
	v_lshlrev_b32_e32 v99, 16, v23
	v_lshlrev_b32_e32 v20, 16, v39
	v_cmp_le_f32_e32 vcc, 0, v20
	v_lshlrev_b32_e32 v21, 16, v40
	v_mul_f32_e64 v30, |v21|, s60
	v_lshlrev_b32_e32 v24, 16, v12
	v_mul_f32_e64 v12, |v20|, s60
	v_exp_f32_e32 v12, v12
	v_exp_f32_e32 v30, v30
	v_lshlrev_b32_e32 v22, 16, v41
	v_lshlrev_b32_e32 v23, 16, v42
	v_lshlrev_b32_e32 v13, 16, v13
	v_add_f32_e32 v31, 1.0, v30
	v_rcp_f32_e32 v31, v31
	v_lshlrev_b32_e32 v14, 16, v14
	v_lshlrev_b32_e32 v15, 16, v15
	v_lshlrev_b32_e32 v95, 16, v27
	v_lshlrev_b32_e32 v92, 16, v29
	global_load_dwordx4 v[2:5], v[2:3], off
	s_nop 0
	global_load_dwordx4 v[6:9], v[6:7], off offset:2560
	v_readfirstlane_b32 s33, v0
	v_lshlrev_b32_e32 v136, 1, v140
	v_mov_b32_e32 v85, v137
	v_lshlrev_b32_e32 v16, 16, v16
	v_lshlrev_b32_e32 v17, 16, v17
	v_lshlrev_b32_e32 v18, 16, v18
	v_lshlrev_b32_e32 v25, 16, v10
	v_add_f32_e32 v10, 1.0, v12
	v_rcp_f32_e32 v26, v10
	v_sub_f32_e32 v10, 1.0, v11
	v_mov_b32_e32 v157, v137
	v_lshlrev_b32_e32 v89, 16, v32
	v_mul_f32_e32 v28, v12, v26
	v_cndmask_b32_e32 v12, v28, v26, vcc
	v_fma_f32 v12, v10, v12, v11
	v_cmp_gt_f32_e64 s[0:1], s61, v12
	v_cndmask_b32_e32 v26, v26, v28, vcc
	v_mul_f32_e32 v102, v10, v26
	v_cndmask_b32_e64 v20, 0, 32, s[0:1]
	v_ldexp_f32 v12, v12, v20
	v_log_f32_e32 v20, v12
	v_lshlrev_b32_e32 v19, 16, v19
	v_lshlrev_b32_e32 v27, 16, v43
	v_lshlrev_b32_e32 v88, 16, v33
	v_mul_f32_e32 v28, 0x3f317217, v20
	v_fma_f32 v28, v20, s62, -v28
	v_fmac_f32_e32 v28, 0x3377d1cf, v20
	v_fmac_f32_e32 v28, 0x3f317217, v20
	v_cmp_lt_f32_e64 vcc, |v20|, s63
	v_lshlrev_b32_e32 v87, 16, v34
	s_waitcnt vmcnt(3)
	v_lshlrev_b32_e32 v29, 16, v38
	v_cndmask_b32_e32 v20, v20, v28, vcc
	v_cndmask_b32_e64 v28, 0, v195, s[0:1]
	v_sub_f32_e32 v20, v20, v28
	v_mul_f32_e32 v28, v30, v31
	v_cmp_le_f32_e32 vcc, 0, v21
	v_add_f32_e32 v103, 0, v20
	s_waitcnt vmcnt(2)
	v_lshlrev_b32_e32 v12, 16, v44
	v_cndmask_b32_e32 v21, v28, v31, vcc
	v_fma_f32 v21, v10, v21, v11
	v_cmp_gt_f32_e64 s[0:1], s61, v21
	v_cndmask_b32_e32 v20, v31, v28, vcc
	v_mul_f32_e64 v28, |v22|, s60
	v_cndmask_b32_e64 v30, 0, 32, s[0:1]
	v_ldexp_f32 v21, v21, v30
	v_log_f32_e32 v21, v21
	v_exp_f32_e32 v28, v28
	v_mul_f32_e32 v104, v10, v20
	v_lshlrev_b32_e32 v86, 16, v35
	v_mul_f32_e32 v26, 0x3f317217, v21
	v_add_f32_e32 v30, 1.0, v28
	v_fma_f32 v26, v21, s62, -v26
	v_rcp_f32_e32 v30, v30
	v_fmac_f32_e32 v26, 0x3377d1cf, v21
	v_fmac_f32_e32 v26, 0x3f317217, v21
	v_cmp_lt_f32_e64 vcc, |v21|, s63
	v_mul_f32_e32 v101, 0x3db504f3, v101
	v_mul_f32_e32 v100, 0x3db504f3, v100
	v_cndmask_b32_e32 v21, v21, v26, vcc
	v_cndmask_b32_e64 v26, 0, v195, s[0:1]
	v_sub_f32_e32 v21, v21, v26
	v_mul_f32_e32 v26, v28, v30
	v_cmp_le_f32_e32 vcc, 0, v22
	v_add_f32_e32 v105, v103, v21
	v_mul_f32_e32 v99, 0x3db504f3, v99
	v_cndmask_b32_e32 v22, v26, v30, vcc
	v_fma_f32 v22, v10, v22, v11
	v_cmp_gt_f32_e64 s[0:1], s61, v22
	v_cndmask_b32_e32 v20, v30, v26, vcc
	v_mul_f32_e64 v26, |v23|, s60
	v_cndmask_b32_e64 v28, 0, 32, s[0:1]
	v_ldexp_f32 v22, v22, v28
	v_log_f32_e32 v22, v22
	v_exp_f32_e32 v26, v26
	v_mul_f32_e32 v106, v10, v20
	v_mul_f32_e32 v98, 0x3db504f3, v98
	v_mul_f32_e32 v21, 0x3f317217, v22
	v_add_f32_e32 v28, 1.0, v26
	v_fma_f32 v21, v22, s62, -v21
	v_rcp_f32_e32 v28, v28
	v_fmac_f32_e32 v21, 0x3377d1cf, v22
	v_fmac_f32_e32 v21, 0x3f317217, v22
	v_cmp_lt_f32_e64 vcc, |v22|, s63
	v_mul_f32_e32 v97, 0x3db504f3, v97
	v_mul_f32_e32 v96, 0x3db504f3, v96
	v_cndmask_b32_e32 v21, v22, v21, vcc
	v_cndmask_b32_e64 v22, 0, v195, s[0:1]
	v_sub_f32_e32 v21, v21, v22
	v_mul_f32_e32 v22, v26, v28
	v_cmp_le_f32_e32 vcc, 0, v23
	v_add_f32_e32 v107, v105, v21
	v_mul_f32_e32 v95, 0x3db504f3, v95
	v_cndmask_b32_e32 v23, v22, v28, vcc
	v_fma_f32 v23, v10, v23, v11
	v_cmp_gt_f32_e64 s[0:1], s61, v23
	v_cndmask_b32_e32 v20, v28, v22, vcc
	v_mul_f32_e64 v22, |v24|, s60
	v_cndmask_b32_e64 v26, 0, 32, s[0:1]
	v_ldexp_f32 v23, v23, v26
	v_exp_f32_e32 v22, v22
	v_log_f32_e32 v23, v23
	v_mul_f32_e32 v108, v10, v20
	v_mul_f32_e32 v94, 0x3db504f3, v94
	v_add_f32_e32 v26, 1.0, v22
	v_mul_f32_e32 v21, 0x3f317217, v23
	v_rcp_f32_e32 v26, v26
	v_fma_f32 v21, v23, s62, -v21
	v_fmac_f32_e32 v21, 0x3377d1cf, v23
	v_fmac_f32_e32 v21, 0x3f317217, v23
	v_cmp_lt_f32_e64 vcc, |v23|, s63
	v_mul_f32_e32 v22, v22, v26
	v_mul_f32_e32 v93, 0x3db504f3, v93
	v_cndmask_b32_e32 v21, v23, v21, vcc
	v_cndmask_b32_e64 v23, 0, v195, s[0:1]
	v_cmp_le_f32_e32 vcc, 0, v24
	v_sub_f32_e32 v21, v21, v23
	v_add_f32_e32 v109, v107, v21
	v_cndmask_b32_e32 v23, v22, v26, vcc
	v_fma_f32 v23, v10, v23, v11
	v_cmp_gt_f32_e64 s[0:1], s61, v23
	v_cndmask_b32_e32 v20, v26, v22, vcc
	v_mul_f32_e64 v22, |v13|, s60
	v_cndmask_b32_e64 v24, 0, 32, s[0:1]
	v_ldexp_f32 v23, v23, v24
	v_exp_f32_e32 v22, v22
	v_log_f32_e32 v23, v23
	v_mul_f32_e32 v110, v10, v20
	v_mul_f32_e32 v92, 0x3db504f3, v92
	v_add_f32_e32 v24, 1.0, v22
	v_mul_f32_e32 v21, 0x3f317217, v23
	v_rcp_f32_e32 v24, v24
	v_fma_f32 v21, v23, s62, -v21
	v_fmac_f32_e32 v21, 0x3377d1cf, v23
	v_fmac_f32_e32 v21, 0x3f317217, v23
	v_cmp_lt_f32_e64 vcc, |v23|, s63
	v_mul_f32_e32 v22, v22, v24
	v_mul_f32_e32 v91, 0x3db504f3, v91
	v_cndmask_b32_e32 v21, v23, v21, vcc
	v_cmp_le_f32_e32 vcc, 0, v13
	v_cndmask_b32_e64 v23, 0, v195, s[0:1]
	v_sub_f32_e32 v21, v21, v23
	v_cndmask_b32_e32 v13, v22, v24, vcc
	v_fma_f32 v13, v10, v13, v11
	v_cmp_gt_f32_e64 s[0:1], s61, v13
	v_cndmask_b32_e32 v20, v24, v22, vcc
	v_mul_f32_e64 v22, |v14|, s60
	v_cndmask_b32_e64 v23, 0, 32, s[0:1]
	v_ldexp_f32 v13, v13, v23
	v_log_f32_e32 v13, v13
	v_exp_f32_e32 v22, v22
	v_add_f32_e32 v111, v109, v21
	v_mul_f32_e32 v112, v10, v20
	v_mul_f32_e32 v21, 0x3f317217, v13
	v_add_f32_e32 v23, 1.0, v22
	v_fma_f32 v21, v13, s62, -v21
	v_rcp_f32_e32 v23, v23
	v_fmac_f32_e32 v21, 0x3377d1cf, v13
	v_fmac_f32_e32 v21, 0x3f317217, v13
	v_cmp_lt_f32_e64 vcc, |v13|, s63
	v_mul_f32_e32 v90, 0x3db504f3, v90
	v_mul_f32_e32 v89, 0x3db504f3, v89
	v_cndmask_b32_e32 v13, v13, v21, vcc
	v_cndmask_b32_e64 v21, 0, v195, s[0:1]
	v_sub_f32_e32 v13, v13, v21
	v_mul_f32_e32 v21, v22, v23
	v_cmp_le_f32_e32 vcc, 0, v14
	v_add_f32_e32 v113, v111, v13
	v_mul_f32_e32 v88, 0x3db504f3, v88
	v_cndmask_b32_e32 v14, v21, v23, vcc
	v_fma_f32 v14, v10, v14, v11
	v_cmp_gt_f32_e64 s[0:1], s61, v14
	v_cndmask_b32_e32 v13, v23, v21, vcc
	v_mul_f32_e64 v21, |v15|, s60
	v_cndmask_b32_e64 v22, 0, 32, s[0:1]
	v_ldexp_f32 v14, v14, v22
	v_log_f32_e32 v14, v14
	v_exp_f32_e32 v21, v21
	v_mul_f32_e32 v121, v10, v13
	v_mul_f32_e32 v87, 0x3db504f3, v87
	v_mul_f32_e32 v20, 0x3f317217, v14
	v_add_f32_e32 v22, 1.0, v21
	v_fma_f32 v20, v14, s62, -v20
	v_rcp_f32_e32 v22, v22
	v_fmac_f32_e32 v20, 0x3377d1cf, v14
	v_fmac_f32_e32 v20, 0x3f317217, v14
	v_cmp_lt_f32_e64 vcc, |v14|, s63
	v_mul_f32_e32 v86, 0x3db504f3, v86
	v_readlane_b32 s73, v255, 14
	v_cndmask_b32_e32 v14, v14, v20, vcc
	v_cndmask_b32_e64 v20, 0, v195, s[0:1]
	v_sub_f32_e32 v14, v14, v20
	v_mul_f32_e32 v20, v21, v22
	v_cmp_le_f32_e32 vcc, 0, v15
	v_add_f32_e32 v120, v113, v14
	v_readlane_b32 s74, v255, 15
	v_cndmask_b32_e32 v15, v20, v22, vcc
	v_fma_f32 v15, v10, v15, v11
	v_cmp_gt_f32_e64 s[0:1], s61, v15
	v_cndmask_b32_e32 v13, v22, v20, vcc
	v_mul_f32_e64 v20, |v16|, s60
	v_cndmask_b32_e64 v21, 0, 32, s[0:1]
	v_ldexp_f32 v15, v15, v21
	v_log_f32_e32 v15, v15
	v_exp_f32_e32 v20, v20
	v_mul_f32_e32 v123, v10, v13
	v_readlane_b32 s75, v255, 16
	v_mul_f32_e32 v14, 0x3f317217, v15
	v_add_f32_e32 v21, 1.0, v20
	v_fma_f32 v14, v15, s62, -v14
	v_rcp_f32_e32 v21, v21
	v_fmac_f32_e32 v14, 0x3377d1cf, v15
	v_fmac_f32_e32 v14, 0x3f317217, v15
	v_cmp_lt_f32_e64 vcc, |v15|, s63
	v_readlane_b32 s78, v255, 19
	v_readlane_b32 s79, v255, 20
	v_cndmask_b32_e32 v14, v15, v14, vcc
	v_cndmask_b32_e64 v15, 0, v195, s[0:1]
	v_sub_f32_e32 v14, v14, v15
	v_mul_f32_e32 v15, v20, v21
	v_cmp_le_f32_e32 vcc, 0, v16
	v_add_f32_e32 v122, v120, v14
	v_readlane_b32 s80, v255, 21
	v_cndmask_b32_e32 v16, v15, v21, vcc
	v_fma_f32 v16, v10, v16, v11
	v_cmp_gt_f32_e64 s[0:1], s61, v16
	v_cndmask_b32_e32 v13, v21, v15, vcc
	v_mul_f32_e64 v15, |v17|, s60
	v_cndmask_b32_e64 v20, 0, 32, s[0:1]
	v_ldexp_f32 v16, v16, v20
	v_exp_f32_e32 v15, v15
	v_log_f32_e32 v16, v16
	v_mul_f32_e32 v125, v10, v13
	v_readlane_b32 s81, v255, 22
	v_add_f32_e32 v20, 1.0, v15
	v_mul_f32_e32 v14, 0x3f317217, v16
	v_rcp_f32_e32 v20, v20
	v_fma_f32 v14, v16, s62, -v14
	v_fmac_f32_e32 v14, 0x3377d1cf, v16
	v_fmac_f32_e32 v14, 0x3f317217, v16
	v_cmp_lt_f32_e64 vcc, |v16|, s63
	v_mul_f32_e32 v15, v15, v20
	v_readlane_b32 s82, v255, 23
	v_cndmask_b32_e32 v14, v16, v14, vcc
	v_cndmask_b32_e64 v16, 0, v195, s[0:1]
	v_cmp_le_f32_e32 vcc, 0, v17
	v_sub_f32_e32 v14, v14, v16
	v_add_f32_e32 v124, v122, v14
	v_cndmask_b32_e32 v16, v15, v20, vcc
	v_fma_f32 v16, v10, v16, v11
	v_cmp_gt_f32_e64 s[0:1], s61, v16
	v_cndmask_b32_e32 v13, v20, v15, vcc
	v_mul_f32_e64 v15, |v18|, s60
	v_cndmask_b32_e64 v17, 0, 32, s[0:1]
	v_ldexp_f32 v16, v16, v17
	v_exp_f32_e32 v15, v15
	v_log_f32_e32 v16, v16
	v_mul_f32_e32 v127, v10, v13
	v_readlane_b32 s83, v255, 24
	v_add_f32_e32 v17, 1.0, v15
	v_mul_f32_e32 v14, 0x3f317217, v16
	v_rcp_f32_e32 v17, v17
	v_fma_f32 v14, v16, s62, -v14
	v_fmac_f32_e32 v14, 0x3377d1cf, v16
	v_fmac_f32_e32 v14, 0x3f317217, v16
	v_cmp_lt_f32_e64 vcc, |v16|, s63
	v_mul_f32_e32 v15, v15, v17
	v_readlane_b32 s84, v255, 25
	v_cndmask_b32_e32 v14, v16, v14, vcc
	v_cndmask_b32_e64 v16, 0, v195, s[0:1]
	v_cmp_le_f32_e32 vcc, 0, v18
	v_sub_f32_e32 v14, v14, v16
	v_add_f32_e32 v126, v124, v14
	v_cndmask_b32_e32 v16, v15, v17, vcc
	v_fma_f32 v16, v10, v16, v11
	v_cmp_gt_f32_e64 s[0:1], s61, v16
	v_cndmask_b32_e32 v13, v17, v15, vcc
	v_mul_f32_e64 v15, |v25|, s60
	v_cndmask_b32_e64 v18, 0, 32, s[0:1]
	v_ldexp_f32 v16, v16, v18
	v_exp_f32_e32 v15, v15
	v_log_f32_e32 v16, v16
	v_mul_f32_e32 v129, v10, v13
	v_readlane_b32 s85, v255, 26
	v_add_f32_e32 v17, 1.0, v15
	v_mul_f32_e32 v14, 0x3f317217, v16
	v_rcp_f32_e32 v17, v17
	v_fma_f32 v14, v16, s62, -v14
	v_fmac_f32_e32 v14, 0x3377d1cf, v16
	v_fmac_f32_e32 v14, 0x3f317217, v16
	v_cmp_lt_f32_e64 vcc, |v16|, s63
	v_mul_f32_e32 v15, v15, v17
	v_readlane_b32 s86, v255, 27
	v_cndmask_b32_e32 v14, v16, v14, vcc
	v_cndmask_b32_e64 v16, 0, v195, s[0:1]
	v_cmp_le_f32_e32 vcc, 0, v25
	v_sub_f32_e32 v14, v14, v16
	v_add_f32_e32 v128, v126, v14
	v_cndmask_b32_e32 v16, v15, v17, vcc
	v_fma_f32 v16, v10, v16, v11
	v_cmp_gt_f32_e64 s[0:1], s61, v16
	v_cndmask_b32_e32 v13, v17, v15, vcc
	v_mul_f32_e64 v15, |v19|, s60
	v_cndmask_b32_e64 v18, 0, 32, s[0:1]
	v_ldexp_f32 v16, v16, v18
	v_exp_f32_e32 v15, v15
	v_log_f32_e32 v16, v16
	v_mul_f32_e32 v131, v10, v13
	v_readlane_b32 s87, v255, 28
	v_add_f32_e32 v17, 1.0, v15
	v_mul_f32_e32 v14, 0x3f317217, v16
	v_rcp_f32_e32 v17, v17
	v_fma_f32 v14, v16, s62, -v14
	v_fmac_f32_e32 v14, 0x3377d1cf, v16
	v_fmac_f32_e32 v14, 0x3f317217, v16
	v_cmp_lt_f32_e64 vcc, |v16|, s63
	v_mul_f32_e32 v15, v15, v17
	s_nop 0
	v_cndmask_b32_e32 v14, v16, v14, vcc
	v_cndmask_b32_e64 v16, 0, v195, s[0:1]
	v_cmp_le_f32_e32 vcc, 0, v19
	v_sub_f32_e32 v14, v14, v16
	v_add_f32_e32 v130, v128, v14
	v_cndmask_b32_e32 v16, v15, v17, vcc
	v_fma_f32 v16, v10, v16, v11
	v_cmp_gt_f32_e64 s[0:1], s61, v16
	v_cndmask_b32_e32 v13, v17, v15, vcc
	v_mul_f32_e64 v15, |v27|, s60
	v_cndmask_b32_e64 v18, 0, 32, s[0:1]
	v_ldexp_f32 v16, v16, v18
	v_exp_f32_e32 v15, v15
	v_log_f32_e32 v16, v16
	v_mul_f32_e32 v133, v10, v13
	v_add_f32_e32 v17, 1.0, v15
	v_mul_f32_e32 v14, 0x3f317217, v16
	v_rcp_f32_e32 v17, v17
	v_fma_f32 v14, v16, s62, -v14
	v_fmac_f32_e32 v14, 0x3377d1cf, v16
	v_fmac_f32_e32 v14, 0x3f317217, v16
	v_cmp_lt_f32_e64 vcc, |v16|, s63
	v_mul_f32_e32 v15, v15, v17
	s_nop 0
	v_cndmask_b32_e32 v14, v16, v14, vcc
	v_cndmask_b32_e64 v16, 0, v195, s[0:1]
	v_cmp_le_f32_e32 vcc, 0, v27
	v_sub_f32_e32 v14, v14, v16
	v_add_f32_e32 v132, v130, v14
	v_cndmask_b32_e32 v16, v15, v17, vcc
	v_fma_f32 v16, v10, v16, v11
	v_cmp_gt_f32_e64 s[0:1], s61, v16
	v_cndmask_b32_e32 v13, v17, v15, vcc
	v_mul_f32_e64 v15, |v29|, s60
	v_cndmask_b32_e64 v18, 0, 32, s[0:1]
	v_ldexp_f32 v16, v16, v18
	v_log_f32_e32 v16, v16
	v_exp_f32_e32 v15, v15
	v_mul_f32_e32 v151, v10, v13
	v_mul_f32_e32 v14, 0x3f317217, v16
	v_add_f32_e32 v17, 1.0, v15
	v_fma_f32 v14, v16, s62, -v14
	v_rcp_f32_e32 v17, v17
	v_fmac_f32_e32 v14, 0x3377d1cf, v16
	v_fmac_f32_e32 v14, 0x3f317217, v16
	v_cmp_lt_f32_e64 vcc, |v16|, s63
	v_mul_f32_e32 v13, v15, v17
	s_nop 0
	v_cndmask_b32_e32 v14, v16, v14, vcc
	v_cndmask_b32_e64 v16, 0, v195, s[0:1]
	v_sub_f32_e32 v14, v14, v16
	v_cmp_le_f32_e32 vcc, 0, v29
	v_add_f32_e32 v149, v132, v14
	s_nop 0
	v_cndmask_b32_e32 v14, v13, v17, vcc
	v_fma_f32 v14, v10, v14, v11
	v_cmp_gt_f32_e64 s[0:1], s61, v14
	s_nop 1
	v_cndmask_b32_e64 v15, 0, 32, s[0:1]
	v_ldexp_f32 v14, v14, v15
	v_cndmask_b32_e32 v15, v17, v13, vcc
	v_mul_f32_e64 v13, |v12|, s60
	v_exp_f32_e32 v13, v13
	v_log_f32_e32 v14, v14
	v_mul_f32_e32 v158, v10, v15
	v_add_f32_e32 v17, 1.0, v13
	v_mul_f32_e32 v16, 0x3f317217, v14
	v_rcp_f32_e32 v17, v17
	v_fma_f32 v16, v14, s62, -v16
	v_fmac_f32_e32 v16, 0x3377d1cf, v14
	v_fmac_f32_e32 v16, 0x3f317217, v14
	v_cmp_lt_f32_e64 vcc, |v14|, s63
	s_nop 1
	v_cndmask_b32_e32 v14, v14, v16, vcc
	v_mul_f32_e32 v16, v13, v17
	v_cmp_le_f32_e32 vcc, 0, v12
	s_nop 1
	v_cndmask_b32_e32 v12, v16, v17, vcc
	v_fmac_f32_e32 v11, v10, v12
	v_cmp_gt_f32_e64 s[20:21], s61, v11
	s_nop 1
	v_cndmask_b32_e64 v12, 0, 32, s[20:21]
	v_ldexp_f32 v11, v11, v12
	v_log_f32_e32 v11, v11
	v_cndmask_b32_e64 v12, 0, v195, s[0:1]
	v_sub_f32_e32 v12, v14, v12
	v_add_f32_e32 v153, v149, v12
	v_mul_f32_e32 v12, 0x3f317217, v11
	v_fma_f32 v12, v11, s62, -v12
	v_fmac_f32_e32 v12, 0x3377d1cf, v11
	v_fmac_f32_e32 v12, 0x3f317217, v11
	v_cmp_lt_f32_e64 s[0:1], |v11|, s63
	s_nop 1
	v_cndmask_b32_e64 v11, v11, v12, s[0:1]
	v_cndmask_b32_e64 v12, 0, v195, s[20:21]
	v_sub_f32_e32 v11, v11, v12
	v_add_f32_e32 v155, v153, v11
	ds_write_b32 v141, v155
	s_waitcnt lgkmcnt(0)
	s_barrier
	ds_read2st64_b32 v[12:13], v143 offset1:2
	v_cndmask_b32_e32 v11, v17, v16, vcc
	s_lshr_b32 s0, s33, 2
	v_mul_f32_e32 v159, v10, v11
	s_and_b32 s68, s0, 0x3fffffc0
	v_lshl_add_u64 v[10:11], s[36:37], 0, v[136:137]
	s_bfe_u32 s37, s33, 0x20006
	ds_read2st64_b32 v[14:15], v143 offset0:4 offset1:6
	s_waitcnt lgkmcnt(1)
	v_add_f32_e32 v117, 0, v12
	v_or_b32_e32 v84, s68, v139
	s_lshl_b32 s36, s37, 4
	v_add_f32_e32 v115, v117, v13
	v_lshlrev_b64 v[12:13], 8, v[84:85]
	v_or_b32_e32 v85, s36, v139
	v_or_b32_e32 v76, s69, v85
	v_mad_i64_i32 v[82:83], s[0:1], v76, s53, v[74:75]
	v_lshl_add_u64 v[74:75], v[82:83], 0, s[40:41]
	s_waitcnt lgkmcnt(0)
	v_add_f32_e32 v114, v115, v14
	v_or_b32_e32 v136, 16, v84
	v_lshl_add_u64 v[74:75], v[74:75], 0, v[156:157]
	s_lshl_b32 s0, s68, 1
	s_mov_b32 s1, s25
	v_add_f32_e32 v116, v114, v15
	v_lshlrev_b64 v[14:15], 8, v[136:137]
	v_or_b32_e32 v136, 32, v84
	v_lshl_add_u64 v[74:75], v[74:75], 0, s[0:1]
	v_lshl_add_u64 v[22:23], v[10:11], 0, v[14:15]
	v_lshlrev_b64 v[14:15], 8, v[136:137]
	v_or_b32_e32 v136, 48, v84
	v_lshl_add_u64 v[118:119], v[74:75], 0, s[34:35]
	v_add_co_u32_e32 v74, vcc, s48, v74
	v_lshl_add_u64 v[26:27], v[10:11], 0, v[14:15]
	v_lshlrev_b64 v[14:15], 8, v[136:137]
	v_addc_co_u32_e32 v75, vcc, 0, v75, vcc
	v_lshl_add_u64 v[12:13], v[10:11], 0, v[12:13]
	v_lshl_add_u64 v[10:11], v[10:11], 0, v[14:15]
	v_cmp_eq_u32_e32 vcc, 1, v1
	s_mul_hi_u32 s99, s67, 0xaaaaaaab
	v_and_b32_e32 v236, 15, v0
	v_bfe_u32 v237, v0, 4, 2
	v_lshrrev_b32_e32 v238, 6, v0
	s_lshr_b32 s99, s99, 3
	s_mul_i32 s100, s99, 12
	s_sub_u32 s100, s67, s100
	s_lshl_b32 s101, s99, 3
	s_add_i32 s101, s101, s100
	s_lshl_b32 s101, s101, 15
	s_add_u32 s0, s90, s101
	s_addc_u32 s1, s91, 0
	v_lshlrev_b32_e32 v239, 8, v236
	v_lshl_add_u32 v239, v237, 4, v239
	v_lshl_add_u32 v239, v238, 12, v239
	global_load_dwordx4 v[200:203], v239, s[0:1]
	global_load_dwordx4 v[204:207], v239, s[0:1] offset:64
	global_load_dwordx4 v[208:211], v239, s[0:1] offset:128
	global_load_dwordx4 v[212:215], v239, s[0:1] offset:192
	s_mul_i32 s99, s99, 0xe8000
	s_lshl_b32 s101, s100, 8
	s_add_i32 s99, s99, s101
	s_addk_i32 s99, 7168
	v_mul_u32_u24_e32 v242, 0x3a00, v236
	v_lshl_add_u32 v242, v237, 3, v242
	v_lshl_add_u32 v242, v238, 5, v242
	v_add_u32_e32 v242, s99, v242
	v_mov_b32_e32 v243, 0
	s_mov_b64 s[98:99], 0x3a000
	v_lshl_add_u64 v[228:229], v[242:243], 0, s[26:27]
	v_lshl_add_u64 v[230:231], v[228:229], 0, s[98:99]
	v_lshl_add_u64 v[232:233], v[230:231], 0, s[98:99]
	v_lshl_add_u64 v[234:235], v[232:233], 0, s[98:99]
	global_load_dwordx2 v[216:217], v[228:229], off offset:-3072
	global_load_dwordx2 v[218:219], v[230:231], off offset:-3072
	global_load_dwordx2 v[220:221], v[232:233], off offset:-3072
	global_load_dwordx2 v[222:223], v[234:235], off offset:-3072
	v_readlane_b32 s98, v255, 19
	v_readlane_b32 s99, v255, 20
	s_lshl_b32 s101, s100, 9
	v_lshl_add_u32 v244, v237, 4, s101
	v_lshl_add_u32 v244, v238, 6, v244
	s_nop 3
	global_load_dwordx4 v[224:227], v244, s[98:99]
	v_cndmask_b32_e32 v118, 0, v117, vcc
	v_cmp_eq_u32_e32 vcc, 2, v1
	s_nop 1
	v_cndmask_b32_e32 v118, v118, v115, vcc
	v_cmp_eq_u32_e32 vcc, 3, v1
	s_nop 1
	v_cndmask_b32_e32 v118, v118, v114, vcc
	v_cmp_eq_u32_e32 vcc, 4, v1
	s_nop 1
	v_cndmask_b32_e32 v116, v118, v116, vcc
	v_mul_f32_e32 v118, 0x3fb8aa3b, v103
	v_exp_f32_e32 v118, v118
	v_mul_f32_e32 v119, 0x3fb8aa3b, v116
	v_exp_f32_e32 v119, v119
	v_mul_f32_e32 v103, 0xbfb8aa3b, v103
	v_mul_f32_e32 v101, v101, v118
	v_cvt_pk_bf16_f32 v118, v101, s0
	ds_write_b16 v191, v118 offset:2560
	v_mul_f32_e32 v118, 0x3fb8aa3b, v105
	v_exp_f32_e32 v118, v118
	v_exp_f32_e32 v103, v103
	v_mul_f32_e32 v101, v101, v119
	v_cvt_pk_bf16_f32 v101, v101, s0
	v_mul_f32_e32 v100, v100, v118
	ds_write_b16 v191, v101 offset:19968
	v_mul_f32_e32 v101, v102, v103
	v_cvt_pk_bf16_f32 v102, v100, s0
	v_mul_f32_e32 v103, 0x3fb8aa3b, v107
	ds_write_b16 v191, v102 offset:2832
	v_mul_f32_e32 v102, 0xbfb8aa3b, v105
	v_exp_f32_e32 v103, v103
	v_exp_f32_e32 v102, v102
	v_mul_f32_e32 v100, v100, v119
	v_cvt_pk_bf16_f32 v100, v100, s0
	v_mul_f32_e32 v99, v99, v103
	ds_write_b16 v191, v100 offset:20240
	v_mul_f32_e32 v100, v104, v102
	v_cvt_pk_bf16_f32 v102, v99, s0
	v_mul_f32_e32 v103, 0x3fb8aa3b, v109
	ds_write_b16 v191, v102 offset:3104
	v_mul_f32_e32 v102, 0xbfb8aa3b, v107
	v_exp_f32_e32 v103, v103
	v_exp_f32_e32 v102, v102
	v_mul_f32_e32 v99, v99, v119
	v_cvt_pk_bf16_f32 v99, v99, s0
	v_mul_f32_e32 v98, v98, v103
	ds_write_b16 v191, v99 offset:20512
	v_mul_f32_e32 v99, v106, v102
	v_cvt_pk_bf16_f32 v102, v98, s0
	v_mul_f32_e32 v103, 0x3fb8aa3b, v111
	ds_write_b16 v191, v102 offset:3376
	v_mul_f32_e32 v102, 0xbfb8aa3b, v109
	v_exp_f32_e32 v103, v103
	v_exp_f32_e32 v102, v102
	v_mul_f32_e32 v98, v98, v119
	v_cvt_pk_bf16_f32 v98, v98, s0
	v_mul_f32_e32 v97, v97, v103
	ds_write_b16 v191, v98 offset:20784
	v_mul_f32_e32 v98, v108, v102
	v_cvt_pk_bf16_f32 v102, v97, s0
	v_mul_f32_e32 v103, 0x3fb8aa3b, v113
	ds_write_b16 v191, v102 offset:3648
	v_mul_f32_e32 v102, 0xbfb8aa3b, v111
	v_exp_f32_e32 v103, v103
	v_exp_f32_e32 v102, v102
	v_mul_f32_e32 v97, v97, v119
	v_cvt_pk_bf16_f32 v97, v97, s0
	v_mul_f32_e32 v96, v96, v103
	ds_write_b16 v191, v97 offset:21056
	v_mul_f32_e32 v97, v110, v102
	v_cvt_pk_bf16_f32 v102, v96, s0
	v_mul_f32_e32 v103, 0x3fb8aa3b, v120
	ds_write_b16 v191, v102 offset:3920
	v_mul_f32_e32 v102, 0xbfb8aa3b, v113
	v_exp_f32_e32 v103, v103
	v_exp_f32_e32 v102, v102
	v_mul_f32_e32 v96, v96, v119
	v_cvt_pk_bf16_f32 v96, v96, s0
	v_mul_f32_e32 v95, v95, v103
	ds_write_b16 v191, v96 offset:21328
	v_mul_f32_e32 v96, v112, v102
	v_cvt_pk_bf16_f32 v102, v95, s0
	v_mul_f32_e32 v103, 0x3fb8aa3b, v122
	ds_write_b16 v191, v102 offset:4192
	v_mul_f32_e32 v102, 0xbfb8aa3b, v120
	v_exp_f32_e32 v103, v103
	v_exp_f32_e32 v102, v102
	v_mul_f32_e32 v95, v95, v119
	v_cvt_pk_bf16_f32 v95, v95, s0
	v_mul_f32_e32 v94, v94, v103
	ds_write_b16 v191, v95 offset:21600
	v_mul_f32_e32 v95, v121, v102
	v_cvt_pk_bf16_f32 v102, v94, s0
	v_mul_f32_e32 v103, 0x3fb8aa3b, v124
	ds_write_b16 v191, v102 offset:4464
	v_mul_f32_e32 v102, 0xbfb8aa3b, v122
	v_exp_f32_e32 v103, v103
	v_exp_f32_e32 v102, v102
	v_mul_f32_e32 v94, v94, v119
	v_cvt_pk_bf16_f32 v94, v94, s0
	v_mul_f32_e32 v93, v93, v103
	ds_write_b16 v191, v94 offset:21872
	v_mul_f32_e32 v94, v123, v102
	v_cvt_pk_bf16_f32 v102, v93, s0
	v_mul_f32_e32 v103, 0x3fb8aa3b, v126
	ds_write_b16 v191, v102 offset:4736
	v_mul_f32_e32 v102, 0xbfb8aa3b, v124
	v_exp_f32_e32 v103, v103
	v_exp_f32_e32 v102, v102
	v_mul_f32_e32 v93, v93, v119
	v_cvt_pk_bf16_f32 v93, v93, s0
	v_mul_f32_e32 v92, v92, v103
	ds_write_b16 v191, v93 offset:22144
	v_mul_f32_e32 v93, v125, v102
	v_cvt_pk_bf16_f32 v102, v92, s0
	v_mul_f32_e32 v103, 0x3fb8aa3b, v128
	ds_write_b16 v191, v102 offset:5008
	v_mul_f32_e32 v102, 0xbfb8aa3b, v126
	v_exp_f32_e32 v103, v103
	v_exp_f32_e32 v102, v102
	v_mul_f32_e32 v92, v92, v119
	v_cvt_pk_bf16_f32 v92, v92, s0
	v_mul_f32_e32 v91, v91, v103
	ds_write_b16 v191, v92 offset:22416
	v_mul_f32_e32 v92, v127, v102
	v_cvt_pk_bf16_f32 v102, v91, s0
	v_mul_f32_e32 v103, 0x3fb8aa3b, v130
	ds_write_b16 v191, v102 offset:5280
	v_mul_f32_e32 v102, 0xbfb8aa3b, v128
	v_exp_f32_e32 v103, v103
	v_exp_f32_e32 v102, v102
	v_mul_f32_e32 v91, v91, v119
	v_cvt_pk_bf16_f32 v91, v91, s0
	v_mul_f32_e32 v90, v90, v103
	ds_write_b16 v191, v91 offset:22688
	v_mul_f32_e32 v91, v129, v102
	v_cvt_pk_bf16_f32 v102, v90, s0
	v_mul_f32_e32 v103, 0x3fb8aa3b, v132
	ds_write_b16 v191, v102 offset:5552
	v_mul_f32_e32 v102, 0xbfb8aa3b, v130
	v_exp_f32_e32 v103, v103
	v_exp_f32_e32 v102, v102
	v_mul_f32_e32 v90, v119, v90
	v_cvt_pk_bf16_f32 v90, v90, s0
	v_mul_f32_e32 v89, v89, v103
	ds_write_b16 v191, v90 offset:22960
	v_mul_f32_e32 v90, v131, v102
	v_cvt_pk_bf16_f32 v102, v89, s0
	v_mul_f32_e32 v103, 0x3fb8aa3b, v149
	ds_write_b16 v191, v102 offset:5824
	v_mul_f32_e32 v102, 0xbfb8aa3b, v132
	v_exp_f32_e32 v103, v103
	v_exp_f32_e32 v102, v102
	v_mul_f32_e32 v89, v119, v89
	v_cvt_pk_bf16_f32 v89, v89, s0
	v_mul_f32_e32 v88, v88, v103
	ds_write_b16 v191, v89 offset:23232
	v_mul_f32_e32 v89, v133, v102
	v_cvt_pk_bf16_f32 v102, v88, s0
	v_mul_f32_e32 v103, 0x3fb8aa3b, v153
	ds_write_b16 v191, v102 offset:6096
	v_mul_f32_e32 v102, 0xbfb8aa3b, v149
	v_exp_f32_e32 v103, v103
	v_exp_f32_e32 v102, v102
	v_mul_f32_e32 v88, v119, v88
	v_cvt_pk_bf16_f32 v88, v88, s0
	v_mul_f32_e32 v87, v87, v103
	ds_write_b16 v191, v88 offset:23504
	v_mul_f32_e32 v88, v151, v102
	v_cvt_pk_bf16_f32 v102, v87, s0
	v_mul_f32_e32 v103, 0x3fb8aa3b, v155
	ds_write_b16 v191, v102 offset:6368
	v_mul_f32_e32 v102, 0xbfb8aa3b, v153
	v_exp_f32_e32 v103, v103
	v_exp_f32_e32 v102, v102
	v_mul_f32_e32 v87, v119, v87
	v_cvt_pk_bf16_f32 v87, v87, s0
	v_mul_f32_e32 v86, v86, v103
	ds_write_b16 v191, v87 offset:23776
	v_mul_f32_e32 v87, v158, v102
	v_cvt_pk_bf16_f32 v102, v86, s0
	ds_write_b16 v191, v102 offset:6640
	v_mul_f32_e32 v102, 0xbfb8aa3b, v155
	v_exp_f32_e32 v102, v102
	v_mul_f32_e32 v86, v119, v86
	v_cvt_pk_bf16_f32 v86, v86, s0
	ds_write_b16 v191, v86 offset:24048
	v_mul_f32_e32 v86, v159, v102
	s_and_saveexec_b64 s[0:1], s[2:3]
	s_cbranch_execnz .LBB0_1397
	s_or_b64 exec, exec, s[0:1]
	s_and_saveexec_b64 s[0:1], s[4:5]
	s_cbranch_execnz .LBB0_1398

.LBB0_1373:
	s_or_b64 exec, exec, s[0:1]
	s_waitcnt vmcnt(10)
	v_and_b32_e32 v86, 0xffff, v2
	v_lshrrev_b32_e32 v2, 16, v2
	s_waitcnt vmcnt(9)
	v_lshl_or_b32 v86, v6, 16, v86
	v_add_u32_e32 v87, v182, v181
	v_and_or_b32 v2, v6, s66, v2
	ds_write2_b32 v87, v86, v2 offset1:36
	v_and_b32_e32 v2, 0xffff, v3
	v_lshrrev_b32_e32 v3, 16, v3
	v_lshl_or_b32 v2, v7, 16, v2
	v_and_or_b32 v3, v7, s66, v3
	ds_write2_b32 v87, v2, v3 offset0:72 offset1:108
	v_and_b32_e32 v2, 0xffff, v4
	v_lshrrev_b32_e32 v3, 16, v4
	v_lshl_or_b32 v2, v8, 16, v2
	v_and_or_b32 v3, v8, s66, v3
	s_lshr_b32 s40, s33, 6
	ds_write2_b32 v87, v2, v3 offset0:144 offset1:180
	v_and_b32_e32 v2, 0xffff, v5
	v_lshrrev_b32_e32 v3, 16, v5
	v_lshl_or_b32 v2, v9, 16, v2
	v_and_or_b32 v3, v9, s66, v3
	s_cmpk_gt_u32 s33, 0x2ff
	ds_write2_b32 v87, v2, v3 offset0:216 offset1:252
	s_waitcnt lgkmcnt(0)
	s_barrier
	s_cbranch_scc1 .LBB0_1382
	s_cmpk_lt_u32 s33, 0x280
	s_mov_b64 s[0:1], -1
	s_cbranch_scc1 .LBB0_1402
	s_andn2_b64 vcc, exec, s[0:1]
	s_cbranch_vccz .LBB0_1403

.LBB0_1390:
	v_mad_u32_u24 v86, v85, s43, v142
	s_waitcnt lgkmcnt(0)
	s_barrier
	v_and_b32_e32 v116, 15, v0
	v_bfe_u32 v117, v0, 4, 2
	v_lshrrev_b32_e32 v118, 6, v0
	v_mul_u32_u24_e32 v119, 0x110, v116
	v_lshl_add_u32 v119, v117, 4, v119
	v_mul_u32_u24_e32 v120, 0x90, v116
	v_lshl_add_u32 v120, v117, 4, v120
	v_mul_u32_u24_e32 v121, 2304, v118
	v_add_u32_e32 v121, v121, v120
	v_add_u32_e32 v121, 0x16000, v121
	v_add_u32_e32 v120, 0x13c00, v120
	v_lshlrev_b32_e32 v123, 5, v116
	v_lshl_add_u32 v122, v118, 2, v123
	v_mov_b32_e32 v124, 0x358637bd
	s_waitcnt vmcnt(0)
	ds_read_b128 v[34:37], v121
	ds_read_b128 v[38:41], v121 offset:64
	ds_read_b128 v[50:53], v119 offset:19968
	ds_read_b128 v[54:57], v119 offset:20032
	ds_read_b128 v[58:61], v119 offset:20096
	ds_read_b128 v[62:65], v119 offset:20160
	ds_read_b128 v[100:103], v120
	ds_read_b128 v[66:69], v119 offset:24320
	ds_read_b128 v[70:73], v119 offset:24384
	ds_read_b128 v[74:77], v119 offset:24448
	ds_read_b128 v[78:81], v119 offset:24512
	ds_read_b128 v[108:111], v120 offset:2304
	s_waitcnt lgkmcnt(5)
	v_mfma_f32_16x16x32_bf16 v[2:5], v[200:203], v[50:53], 0
	v_mfma_f32_16x16x32_bf16 v[2:5], v[204:207], v[54:57], v[2:5]
	v_mfma_f32_16x16x32_bf16 v[2:5], v[208:211], v[58:61], v[2:5]
	v_mfma_f32_16x16x32_bf16 v[2:5], v[212:215], v[62:65], v[2:5]
	v_mfma_f32_16x16x32_bf16 v[2:5], v[34:37], v[100:103], v[2:5]
	ds_read_b128 v[50:53], v119 offset:28672
	ds_read_b128 v[54:57], v119 offset:28736
	ds_read_b128 v[58:61], v119 offset:28800
	ds_read_b128 v[62:65], v119 offset:28864
	ds_read_b128 v[100:103], v120 offset:4608
	ds_read_b128 v[104:107], v120 offset:4672
	s_waitcnt lgkmcnt(6)
	v_mfma_f32_16x16x32_bf16 v[6:9], v[200:203], v[66:69], 0
	v_mfma_f32_16x16x32_bf16 v[6:9], v[204:207], v[70:73], v[6:9]
	v_mfma_f32_16x16x32_bf16 v[6:9], v[208:211], v[74:77], v[6:9]
	v_mfma_f32_16x16x32_bf16 v[6:9], v[212:215], v[78:81], v[6:9]
	v_mfma_f32_16x16x32_bf16 v[6:9], v[34:37], v[108:111], v[6:9]
	ds_read_b128 v[66:69], v119 offset:33024
	ds_read_b128 v[70:73], v119 offset:33088
	ds_read_b128 v[74:77], v119 offset:33152
	ds_read_b128 v[78:81], v119 offset:33216
	ds_read_b128 v[108:111], v120 offset:6912
	ds_read_b128 v[112:115], v120 offset:6976
	s_waitcnt lgkmcnt(6)
	v_mfma_f32_16x16x32_bf16 v[10:13], v[200:203], v[50:53], 0
	v_mfma_f32_16x16x32_bf16 v[10:13], v[204:207], v[54:57], v[10:13]
	v_mfma_f32_16x16x32_bf16 v[10:13], v[208:211], v[58:61], v[10:13]
	v_mfma_f32_16x16x32_bf16 v[10:13], v[212:215], v[62:65], v[10:13]
	v_mfma_f32_16x16x32_bf16 v[10:13], v[34:37], v[100:103], v[10:13]
	v_mfma_f32_16x16x32_bf16 v[10:13], v[38:41], v[104:107], v[10:13]
	s_waitcnt lgkmcnt(0)
	v_mfma_f32_16x16x32_bf16 v[14:17], v[200:203], v[66:69], 0
	v_mfma_f32_16x16x32_bf16 v[14:17], v[204:207], v[70:73], v[14:17]
	v_mfma_f32_16x16x32_bf16 v[14:17], v[208:211], v[74:77], v[14:17]
	v_mfma_f32_16x16x32_bf16 v[14:17], v[212:215], v[78:81], v[14:17]
	v_mfma_f32_16x16x32_bf16 v[14:17], v[34:37], v[108:111], v[14:17]
	v_mfma_f32_16x16x32_bf16 v[14:17], v[38:41], v[112:115], v[14:17]
	s_nop 7
	s_nop 1
	v_mul_f32_e32 v125, v2, v2
	v_fmac_f32_e32 v125, v3, v3
	v_fmac_f32_e32 v125, v4, v4
	v_fmac_f32_e32 v125, v5, v5
	v_mul_f32_e32 v126, v6, v6
	v_fmac_f32_e32 v126, v7, v7
	v_fmac_f32_e32 v126, v8, v8
	v_fmac_f32_e32 v126, v9, v9
	v_mul_f32_e32 v127, v10, v10
	v_fmac_f32_e32 v127, v11, v11
	v_fmac_f32_e32 v127, v12, v12
	v_fmac_f32_e32 v127, v13, v13
	v_mul_f32_e32 v128, v14, v14
	v_fmac_f32_e32 v128, v15, v15
	v_fmac_f32_e32 v128, v16, v16
	v_fmac_f32_e32 v128, v17, v17
	ds_swizzle_b32 v129, v125 offset:0x401F
	ds_swizzle_b32 v130, v126 offset:0x401F
	ds_swizzle_b32 v131, v127 offset:0x401F
	ds_swizzle_b32 v132, v128 offset:0x401F
	s_waitcnt lgkmcnt(0)
	v_add_f32_e32 v125, v125, v129
	v_add_f32_e32 v126, v126, v130
	v_add_f32_e32 v127, v127, v131
	v_add_f32_e32 v128, v128, v132
	v_mov_b32_e32 v129, v125
	v_mov_b32_e32 v130, v126
	v_mov_b32_e32 v131, v127
	v_mov_b32_e32 v132, v128
	s_nop 1
	v_permlane32_swap_b32_e32 v129, v125
	v_permlane32_swap_b32_e32 v130, v126
	v_permlane32_swap_b32_e32 v131, v127
	v_permlane32_swap_b32_e32 v132, v128
	s_nop 1
	v_add_f32_e32 v125, v125, v129
	v_add_f32_e32 v126, v126, v130
	v_add_f32_e32 v127, v127, v131
	v_add_f32_e32 v128, v128, v132
	ds_write_b32 v122, v125
	ds_write_b32 v122, v126 offset:512
	ds_write_b32 v122, v127 offset:1024
	ds_write_b32 v122, v128 offset:1536
	s_waitcnt lgkmcnt(0)
	s_barrier
	ds_read_b128 v[50:53], v123
	ds_read_b128 v[54:57], v123 offset:16
	ds_read_b128 v[58:61], v123 offset:512
	ds_read_b128 v[62:65], v123 offset:528
	ds_read_b128 v[66:69], v123 offset:1024
	ds_read_b128 v[70:73], v123 offset:1040
	ds_read_b128 v[74:77], v123 offset:1536
	ds_read_b128 v[78:81], v123 offset:1552
	s_waitcnt lgkmcnt(0)
	s_barrier
	v_add_f32_e32 v50, v50, v51
	v_add_f32_e32 v52, v52, v53
	v_add_f32_e32 v54, v54, v55
	v_add_f32_e32 v56, v56, v57
	v_add_f32_e32 v50, v50, v52
	v_add_f32_e32 v54, v54, v56
	v_add_f32_e32 v50, v50, v54
	v_fmamk_f32 v50, v50, 0x3c000000, v124
	v_rsq_f32_e32 v125, v50
	v_add_f32_e32 v58, v58, v59
	v_add_f32_e32 v60, v60, v61
	v_add_f32_e32 v62, v62, v63
	v_add_f32_e32 v64, v64, v65
	v_add_f32_e32 v58, v58, v60
	v_add_f32_e32 v62, v62, v64
	v_add_f32_e32 v58, v58, v62
	v_fmamk_f32 v58, v58, 0x3c000000, v124
	v_rsq_f32_e32 v126, v58
	v_add_f32_e32 v66, v66, v67
	v_add_f32_e32 v68, v68, v69
	v_add_f32_e32 v70, v70, v71
	v_add_f32_e32 v72, v72, v73
	v_add_f32_e32 v66, v66, v68
	v_add_f32_e32 v70, v70, v72
	v_add_f32_e32 v66, v66, v70
	v_fmamk_f32 v66, v66, 0x3c000000, v124
	v_rsq_f32_e32 v127, v66
	v_add_f32_e32 v74, v74, v75
	v_add_f32_e32 v76, v76, v77
	v_add_f32_e32 v78, v78, v79
	v_add_f32_e32 v80, v80, v81
	v_add_f32_e32 v74, v74, v76
	v_add_f32_e32 v78, v78, v80
	v_add_f32_e32 v74, v74, v78
	v_fmamk_f32 v74, v74, 0x3c000000, v124
	v_rsq_f32_e32 v128, v74
	v_lshlrev_b32_e32 v66, 16, v216
	v_and_b32_e32 v67, 0xffff0000, v216
	v_lshlrev_b32_e32 v68, 16, v217
	v_and_b32_e32 v69, 0xffff0000, v217
	v_mul_f32_e32 v2, v2, v125
	v_mul_f32_e32 v3, v3, v125
	v_mul_f32_e32 v4, v4, v125
	v_mul_f32_e32 v5, v5, v125
	v_mul_f32_e32 v2, v2, v224
	v_mul_f32_e32 v3, v3, v225
	v_mul_f32_e32 v4, v4, v226
	v_mul_f32_e32 v5, v5, v227
	v_mul_f32_e32 v2, v2, v66
	v_mul_f32_e32 v3, v3, v67
	v_mul_f32_e32 v4, v4, v68
	v_mul_f32_e32 v5, v5, v69
	v_cvt_pk_bf16_f32 v2, v2, v3
	v_cvt_pk_bf16_f32 v3, v4, v5
	global_store_dwordx2 v[228:229], v[2:3], off offset:3072
	v_lshlrev_b32_e32 v66, 16, v218
	v_and_b32_e32 v67, 0xffff0000, v218
	v_lshlrev_b32_e32 v68, 16, v219
	v_and_b32_e32 v69, 0xffff0000, v219
	v_mul_f32_e32 v6, v6, v126
	v_mul_f32_e32 v7, v7, v126
	v_mul_f32_e32 v8, v8, v126
	v_mul_f32_e32 v9, v9, v126
	v_mul_f32_e32 v6, v6, v224
	v_mul_f32_e32 v7, v7, v225
	v_mul_f32_e32 v8, v8, v226
	v_mul_f32_e32 v9, v9, v227
	v_mul_f32_e32 v6, v6, v66
	v_mul_f32_e32 v7, v7, v67
	v_mul_f32_e32 v8, v8, v68
	v_mul_f32_e32 v9, v9, v69
	v_cvt_pk_bf16_f32 v6, v6, v7
	v_cvt_pk_bf16_f32 v7, v8, v9
	global_store_dwordx2 v[230:231], v[6:7], off offset:3072
	v_lshlrev_b32_e32 v66, 16, v220
	v_and_b32_e32 v67, 0xffff0000, v220
	v_lshlrev_b32_e32 v68, 16, v221
	v_and_b32_e32 v69, 0xffff0000, v221
	v_mul_f32_e32 v10, v10, v127
	v_mul_f32_e32 v11, v11, v127
	v_mul_f32_e32 v12, v12, v127
	v_mul_f32_e32 v13, v13, v127
	v_mul_f32_e32 v10, v10, v224
	v_mul_f32_e32 v11, v11, v225
	v_mul_f32_e32 v12, v12, v226
	v_mul_f32_e32 v13, v13, v227
	v_mul_f32_e32 v10, v10, v66
	v_mul_f32_e32 v11, v11, v67
	v_mul_f32_e32 v12, v12, v68
	v_mul_f32_e32 v13, v13, v69
	v_cvt_pk_bf16_f32 v10, v10, v11
	v_cvt_pk_bf16_f32 v11, v12, v13
	global_store_dwordx2 v[232:233], v[10:11], off offset:3072
	v_lshlrev_b32_e32 v66, 16, v222
	v_and_b32_e32 v67, 0xffff0000, v222
	v_lshlrev_b32_e32 v68, 16, v223
	v_and_b32_e32 v69, 0xffff0000, v223
	v_mul_f32_e32 v14, v14, v128
	v_mul_f32_e32 v15, v15, v128
	v_mul_f32_e32 v16, v16, v128
	v_mul_f32_e32 v17, v17, v128
	v_mul_f32_e32 v14, v14, v224
	v_mul_f32_e32 v15, v15, v225
	v_mul_f32_e32 v16, v16, v226
	v_mul_f32_e32 v17, v17, v227
	v_mul_f32_e32 v14, v14, v66
	v_mul_f32_e32 v15, v15, v67
	v_mul_f32_e32 v16, v16, v68
	v_mul_f32_e32 v17, v17, v69
	v_cvt_pk_bf16_f32 v14, v14, v15
	v_cvt_pk_bf16_f32 v15, v16, v17
	global_store_dwordx2 v[234:235], v[14:15], off offset:3072
	s_branch .LBB0_1338

	.amdhsa_kernel _Z4mega6Params
		.amdhsa_group_segment_fixed_size 0
		.amdhsa_private_segment_fixed_size 0
		.amdhsa_kernarg_size 448
		.amdhsa_user_sgpr_count 2
		.amdhsa_user_sgpr_dispatch_ptr 0
		.amdhsa_user_sgpr_queue_ptr 0
		.amdhsa_user_sgpr_kernarg_segment_ptr 1
		.amdhsa_user_sgpr_dispatch_id 0
		.amdhsa_user_sgpr_kernarg_preload_length 0
		.amdhsa_user_sgpr_kernarg_preload_offset 0
		.amdhsa_user_sgpr_private_segment_size 0
		.amdhsa_uses_dynamic_stack 0
		.amdhsa_enable_private_segment 0
		.amdhsa_system_sgpr_workgroup_id_x 1
		.amdhsa_system_sgpr_workgroup_id_y 0
		.amdhsa_system_sgpr_workgroup_id_z 0
		.amdhsa_system_sgpr_workgroup_info 0
		.amdhsa_system_vgpr_workitem_id 0
		.amdhsa_next_free_vgpr 256
		.amdhsa_next_free_sgpr 102
		.amdhsa_accum_offset 256
		.amdhsa_reserve_vcc 1
		.amdhsa_float_round_mode_32 0
		.amdhsa_float_round_mode_16_64 0
		.amdhsa_float_denorm_mode_32 3
		.amdhsa_float_denorm_mode_16_64 3
		.amdhsa_dx10_clamp 1
		.amdhsa_ieee_mode 1
		.amdhsa_fp16_overflow 0
		.amdhsa_tg_split 0
		.amdhsa_exception_fp_ieee_invalid_op 0
		.amdhsa_exception_fp_denorm_src 0
		.amdhsa_exception_fp_ieee_div_zero 0
		.amdhsa_exception_fp_ieee_overflow 0
		.amdhsa_exception_fp_ieee_underflow 0
		.amdhsa_exception_fp_ieee_inexact 0
		.amdhsa_exception_int_div_zero 0
	.end_amdhsa_kernel

amdhsa.kernels:
  - .agpr_count:     0
    .args:
      - .offset:         0
        .size:           192
        .value_kind:     by_value
      - .offset:         192
        .size:           4
        .value_kind:     hidden_block_count_x
      - .offset:         196
        .size:           4
        .value_kind:     hidden_block_count_y
      - .offset:         200
        .size:           4
        .value_kind:     hidden_block_count_z
      - .offset:         204
        .size:           2
        .value_kind:     hidden_group_size_x
      - .offset:         206
        .size:           2
        .value_kind:     hidden_group_size_y
      - .offset:         208
        .size:           2
        .value_kind:     hidden_group_size_z
      - .offset:         210
        .size:           2
        .value_kind:     hidden_remainder_x
      - .offset:         212
        .size:           2
        .value_kind:     hidden_remainder_y
      - .offset:         214
        .size:           2
        .value_kind:     hidden_remainder_z
      - .offset:         232
        .size:           8
        .value_kind:     hidden_global_offset_x
      - .offset:         240
        .size:           8
        .value_kind:     hidden_global_offset_y
      - .offset:         248
        .size:           8
        .value_kind:     hidden_global_offset_z
      - .offset:         256
        .size:           2
        .value_kind:     hidden_grid_dims
      - .offset:         312
        .size:           4
        .value_kind:     hidden_dynamic_lds_size
    .group_segment_fixed_size: 0
    .kernarg_segment_align: 8
    .kernarg_segment_size: 448
    .language:       OpenCL C
    .language_version:
      - 2
      - 0
    .max_flat_workgroup_size: 512
    .name:           _Z4mega6Params
    .private_segment_fixed_size: 0
    .sgpr_count:     108
    .sgpr_spill_count: 36
    .symbol:         _Z4mega6Params.kd
    .uniform_work_group_size: 1
    .uses_dynamic_stack: false
    .vgpr_count:     256
    .vgpr_spill_count: 0
    .wavefront_size: 64
